# loop-edge rotation (7.11): block-loop and compressed-step bookkeeping moved ahead of the barrier, only the branch follows the rendezvous
# speedup vs baseline: 1.0054x; 1.0016x over previous
; #define LAS __attribute__((address_space(3)))
; __device__ __forceinline__ void nsa_quad_pre(int bg, int quad, const bf16_t* Q, const bf16_t* KV, const bf16_t* KCMP, const bf16_t* VCMPT, const float* GN, bf16_t* ONSA, ...
;     const int r16 = lane & 15, q4 = lane >> 4, b = bg >> 2, g = bg & 3, t0 = quad * 4;
;     const unsigned koff = (unsigned)(r16 * 64 + q4 * 8) * 2u, voffS = (unsigned)(r16 * SEQ + q4 * 8) * 2u, voffC = (unsigned)(r16 * 512 + q4 * 8) * 2u;
;     const char* KWb = (const char*)(KV + 4 * (size_t)MTOK * 256 + (size_t)bg * SEQ * 64); const char* VWb = (const char*)(KV + 5 * (size_t)MTOK * 256 + (size_t)bg * 64 * SEQ);
;     const char* KCb = (const char*)(KCMP + (size_t)bg * 512 * 64); const char* VCb = (const char*)(VCMPT + (size_t)bg * 64 * 512);
;     ...
;     const size_t qoff = (size_t)(b * SEQ + t0 + (r16 & 3)) * 1024 + (g * 4 + (r16 >> 2)) * 64 + q4 * 8;
;     { const bf16x8 a0 = *(const bf16x8*)(Q + qoff), a1 = *(const bf16x8*)(Q + qoff + 32); *(LAS bf16x8*)(qfw + lane * 8) = a0; *(LAS bf16x8*)(qfw + 512 + lane * 8) = a1; }
;     const LAS bf16_t* qf = qfw + lane * 8;
;     const LAS float* bt = btab + q4 * 1028;
;     const f32x4 z4 = {0.f, 0.f, 0.f, 0.f};
;     KFrag KF; VFrag VF; f32x4 sc[4];
;     const int w_lo = (t0 - 511 > 0 ? t0 - 511 : 0) >> 6, w_hi = t0 >> 6;
;     f32x4 oc[4] = {z4, z4, z4, z4};
;     const int tl = t0 + 3, nvmax = tl >= 31 ? ((tl - 31) >> 4) + 1 : 0, ngr = (nvmax + 63) >> 6;
;     if (ngr > 0) {
;         float ls[4] = {0.f, 0.f, 0.f, 0.f};
;         load_k(KF, KP_C(0));
; __device__ __forceinline__ void nsa_phase(LAS unsigned char* lds, const bf16_t* Q, const bf16_t* KV, const bf16_t* KCMP, const bf16_t* VCMPT, const float* GN, const float* rel_bias, bf16_t* ONSA,
;                                           int tid, int lane, int wave) {
;     ...
;                 const int qb = (kk & 1) ? (32 * kk + 31 - idx) : (32 * kk + idx);
;                 nsa_quad_pre(bg, qb * 16 + wave * 2, Q, KV, KCMP, VCMPT, GN, ONSA, btab, Pb, psum, selall + (wave * 2) * 64, qfw, lane);
.LBB0_738:
	s_lshl_b32 s1, s3, 5
	s_sub_i32 s14, s1, s91
	s_and_b32 s0, s3, 1
	s_add_i32 s14, s14, 31
	s_add_i32 s1, s1, s91
	s_cmp_eq_u32 s0, 0
	s_cselect_b32 s18, s1, s14
	v_and_b32_e32 v232, 15, v184
	v_lshrrev_b32_e32 v233, 4, v184
	v_and_b32_e32 v234, 3, v232
	v_lshrrev_b32_e32 v235, 2, v232
	v_mul_u32_u24_e32 v173, 0x1010, v235
	ds_read_b32 v225, v173 offset:4096
	v_mov_b32_e32 v252, 0xf149f2ca
	v_and_b32_e32 v253, 1, v235
	v_xor_b32_e32 v0, v233, v234
	v_lshlrev_b32_e32 v0, 4, v0
	v_lshl_add_u32 v0, v253, 6, v0
	v_lshl_add_u32 v98, v235, 3, v234
	v_lshl_add_u32 v176, v98, 7, v0
	s_lshl_b32 s33, s80, 7
	v_lshl_add_u32 v177, v232, 7, v0
	v_subrev_u32_e32 v177, s33, v177
	v_lshlrev_b32_e32 v98, 7, v253
	v_sub_u32_e32 v178, 64, v98
	v_lshrrev_b32_e32 v98, 3, v184
	v_and_b32_e32 v99, 7, v184
	s_lshr_b32 s0, s80, 3
	s_and_b32 s1, s0, 1
	s_lshl_b32 s1, s1, 2
	v_and_b32_e32 v253, 3, v98
	v_or_b32_e32 v253, s1, v253
	v_xor_b32_e32 v253, v99, v253
	v_add_u32_e32 v0, s80, v98
	v_lshlrev_b32_e32 v174, 7, v0
	v_lshl_add_u32 v174, v253, 4, v174
	v_xor_b32_e32 v253, v99, v98
	v_lshlrev_b32_e32 v175, 10, v0
	v_lshl_add_u32 v175, v253, 4, v175
	s_add_i32 s94, s33, 0xa040
	s_add_i32 s95, s33, 0x1dc40
	s_add_i32 s46, s33, 0x20200
	s_lshr_b32 s15, s97, 13
	s_lshl_b32 s15, s15, 2
	s_and_b32 s1, s88, 3
	s_or_b32 s15, s15, s1
	s_lshl_b32 s15, s15, 16
	s_add_u32 s68, s30, 0x38110000
	s_addc_u32 s69, s31, 0
	s_add_u32 s68, s68, s15
	s_addc_u32 s69, s69, 0
	s_add_u32 s70, s30, 0x38210000
	s_addc_u32 s71, s31, 0
	s_add_u32 s70, s70, s15
	s_addc_u32 s71, s71, 0
	s_lshl_b32 s74, s18, 2
	s_add_i32 s74, s74, 66
	s_lshr_b32 s74, s74, 6
	s_mov_b32 s75, 0
	v_lshlrev_b32_e32 v98, 7, v233
	v_sub_u32_e32 v172, v234, v98
	v_add_u32_e32 v172, 0xffffffe1, v172
	s_lshl_b32 s0, s80, 10
	s_add_i32 s0, s0, 56384
	v_lshlrev_b32_e32 v215, 11, v234
	v_lshl_add_u32 v215, v233, 5, v215
	v_add_u32_e32 v215, s0, v215
	s_mov_b32 s92, 0
	s_mov_b32 s93, 0
	s_lshl_b32 s0, s92, 13
	s_add_i32 s0, s0, s33
	s_add_i32 m0, s0, 16448
	s_lshl_b32 s1, s93, 13
	s_add_u32 s72, s68, s1
	s_addc_u32 s73, s69, 0
	global_load_lds_dwordx4 v174, s[72:73]
	s_cmp_eq_u32 s92, 1
	s_cselect_b32 s0, s95, s94
	s_cmp_eq_u32 s92, 2
	s_cselect_b32 m0, s46, s0
	s_lshl_b32 s1, s93, 7
	s_add_u32 s72, s70, s1
	s_addc_u32 s73, s71, 0
	global_load_lds_dwordx4 v175, s[72:73]
	s_add_i32 s93, s93, 1
	s_cmp_ge_i32 s93, s74
	s_cselect_b32 s93, 0, s93
	s_add_i32 s92, s92, 1
	s_cmp_eq_u32 s92, 3
	s_cselect_b32 s92, 0, s92
	s_lshl_b32 s0, s92, 13
	s_add_i32 s0, s0, s33
	s_add_i32 m0, s0, 16448
	s_lshl_b32 s1, s93, 13
	s_add_u32 s72, s68, s1
	s_addc_u32 s73, s69, 0
	global_load_lds_dwordx4 v174, s[72:73]
	s_cmp_eq_u32 s92, 1
	s_cselect_b32 s0, s95, s94
	s_cmp_eq_u32 s92, 2
	s_cselect_b32 m0, s46, s0
	s_lshl_b32 s1, s93, 7
	s_add_u32 s72, s70, s1
	s_addc_u32 s73, s71, 0
	global_load_lds_dwordx4 v175, s[72:73]
	s_add_i32 s93, s93, 1
	s_cmp_ge_i32 s93, s74
	s_cselect_b32 s93, 0, s93
	s_add_i32 s92, s92, 1
	s_cmp_eq_u32 s92, 3
	s_cselect_b32 s92, 0, s92
	s_lshl_b32 s0, s18, 6
	s_add_i32 s0, s0, s97
	s_add_i32 s0, s0, s80
	v_add_u32_e32 v253, s0, v234
	s_and_b32 s1, s88, 3
	s_lshl_b32 s1, s1, 2
	v_add_u32_e32 v98, s1, v235
	v_lshlrev_b32_e32 v98, 7, v98
	v_lshl_add_u32 v98, v253, 11, v98
	v_lshl_add_u32 v98, v233, 4, v98
	v_add_u32_e32 v99, 0x2000, v98
	s_add_u32 s72, s30, 0x29900000
	s_addc_u32 s73, s31, 0
	global_load_dwordx4 v[34:37], v98, s[72:73] offset:0
	global_load_dwordx4 v[38:41], v98, s[72:73] offset:64
	global_load_dwordx4 v[42:45], v99, s[72:73] offset:0
	global_load_dwordx4 v[46:49], v99, s[72:73] offset:64
	s_waitcnt lgkmcnt(0)
	s_lshl_b32 s47, s18, 6
	s_add_i32 s47, s47, s80
	v_and_b32_e32 v232, 15, v184
	v_and_b32_e32 v234, 3, v232
	v_lshrrev_b32_e32 v235, 2, v232
	s_add_i32 s0, s47, s97
	v_add_u32_e32 v253, s0, v234
	s_and_b32 s1, s88, 3
	s_lshl_b32 s1, s1, 2
	v_add_u32_e32 v0, s1, v235
	v_mul_u32_u24_e32 v99, 0xc0, v253
	v_mul_u32_u24_e32 v0, 12, v0
	v_add_u32_e32 v99, v99, v0
	s_add_u32 s72, s30, 0x38310000
	s_addc_u32 s73, s31, 0
	global_load_dword v227, v99, s[72:73]
	v_mov_b32_e32 v2, 0
	v_mov_b32_e32 v3, 0
	v_mov_b32_e32 v4, 0
	v_mov_b32_e32 v5, 0
	v_mov_b32_e32 v6, 0
	v_mov_b32_e32 v7, 0
	v_mov_b32_e32 v8, 0
	v_mov_b32_e32 v9, 0
	v_mov_b32_e32 v10, 0
	v_mov_b32_e32 v11, 0
	v_mov_b32_e32 v12, 0
	v_mov_b32_e32 v13, 0
	v_mov_b32_e32 v14, 0
	v_mov_b32_e32 v15, 0
	v_mov_b32_e32 v16, 0
	v_mov_b32_e32 v17, 0
	s_sub_i32 s0, s47, 28
	s_ashr_i32 s0, s0, 4
	s_add_i32 s0, s0, 64
	s_ashr_i32 s53, s0, 6
	s_cmp_gt_i32 s47, 27
	s_cselect_b32 s53, s53, 0
	s_sub_i32 s0, s47, 2063
	s_ashr_i32 s52, s0, 10
	s_add_i32 s52, s52, 1
	s_max_i32 s52, s52, 0
	s_min_i32 s52, s52, s53
	v_add_u32_e32 v99, s47, v172
	v_and_b32_e32 v98, 15, v184
	v_mov_b32_e32 v170, 0
	s_waitcnt vmcnt(0)
	s_barrier
	s_mov_b32 s57, 0

; __device__ __forceinline__ float red16(float v) { v += __shfl_xor(v, 1); v += __shfl_xor(v, 2); v += __shfl_xor(v, 4); v += __shfl_xor(v, 8); return v; }
; __device__ __forceinline__ void nsa_quad_pre(int bg, int quad, const bf16_t* Q, const bf16_t* KV, const bf16_t* KCMP, const bf16_t* VCMPT, const float* GN, bf16_t* ONSA, ...
;     ...
;         load_k(KF, KP_C(0));
;         for (int gr = 0; gr < ngr; ++gr) {
;             qk_scores(KF, qf, sc);
;             load_k(KF, KP_C(gr + 1 < ngr ? gr + 1 : 0));
;             cmp_sm1(sc, gr, t0, bt, ls, r16);
;         }
;         load_v(VF, VP_C(0));
;         float inv[4];
; #pragma unroll
;         for (int i = 0; i < 4; ++i) { const float l = red16(ls[i]); inv[i] = l > 0.f ? 1.f / l : 0.f; }
.Lcmp_tail_q0p1:
	s_add_i32 s75, s75, 1
	s_cmp_eq_u32 s75, 3
	s_cselect_b32 s75, 0, s75
	s_add_i32 s57, s57, 1
	s_cmp_lt_i32 s57, s74
	s_waitcnt vmcnt(2)
	s_barrier
	s_cbranch_scc1 .Lcmp_top_q0p1
	v_xor_b32_e32 v232, 16, v184
	v_lshlrev_b32_e32 v232, 2, v232
	v_xor_b32_e32 v233, 32, v184
	v_lshlrev_b32_e32 v233, 2, v233
	ds_bpermute_b32 v234, v232, v170
	s_waitcnt lgkmcnt(0)
	v_add_f32_e32 v170, v170, v234
	ds_bpermute_b32 v234, v233, v170
	s_waitcnt lgkmcnt(0)
	v_add_f32_e32 v170, v170, v234
	v_mov_b32_e32 v0, 1.0
	v_div_scale_f32 v232, s[20:21], v170, v170, v0
	v_rcp_f32_e32 v233, v232
	v_div_scale_f32 v234, vcc, v0, v170, v0
	v_fma_f32 v235, -v232, v233, 1.0
	v_fmac_f32_e32 v233, v235, v233
	v_mul_f32_e32 v235, v234, v233
	v_fma_f32 v253, -v232, v235, v234
	v_fmac_f32_e32 v235, v253, v233
	v_fma_f32 v232, -v232, v235, v234
	s_nop 1
	v_div_fmas_f32 v232, v232, v233, v235
	v_div_fixup_f32 v171, v232, v170, v0
	v_cmp_lt_f32_e32 vcc, 0, v170
	s_nop 1
	v_cndmask_b32_e32 v171, 0, v171, vcc
	s_mov_b32 s57, 0

; #define LAS __attribute__((address_space(3)))
; #define CBAR() asm volatile("" ::: "memory")
; __device__ __forceinline__ bf16_t tobf(float x) { return (bf16_t)pk2(x, 0.f); }
; __device__ __forceinline__ void nsa_quad_pre(int bg, int quad, const bf16_t* Q, const bf16_t* KV, const bf16_t* KCMP, const bf16_t* VCMPT, const float* GN, bf16_t* ONSA, ...
;     ...
;         for (int gr = 0; gr < ngr; ++gr) {
;             const bool more = gr + 1 < ngr;
;             qk_scores(KF, qf, sc);
;             if (more) load_k(KF, KP_C(gr + 1));
;             cmp_sm2(sc, gr, t0, bt, inv, Pb, psum, r16, q4);
;             pv_step(VF, oc, Pb, r16, q4);
;             if (more) load_v(VF, VP_C(gr + 1));
;         }
;     }
;     CBAR();
; #pragma unroll
;     for (int tt = 0; tt < 4; ++tt) {
;         const int tok = t0 + tt, cur = tok >> 6;
;         if (cur < 16) { if (lane < 16) selq[tt * 16 + lane] = lane; }
;         else {
;             unsigned k0 = 0u, k1 = 0u;
;             { const int j = lane; if (j >= 1 && j <= cur - 2) { const LAS float* ps = psum + tt * 512 + 4 * j - 1; const float v = ps[0] + ps[1] + ps[2] + ps[3] + ps[4]; k0 = (__builtin_bit_cast(unsigned, v) & ~127u) | (unsigned)(127 - j); } }
;             { const int j = lane + 64; if (j <= cur - 2) { const LAS float* ps = psum + tt * 512 + 4 * j - 1; const float v = ps[0] + ps[1] + ps[2] + ps[3] + ps[4]; k1 = (__builtin_bit_cast(unsigned, v) & ~127u) | (unsigned)(127 - j); } }
;             for (int it = 0; it < 13; ++it) {
;                 unsigned m = k0 > k1 ? k0 : k1;
; #pragma unroll
;                 for (int off = 32; off >= 1; off >>= 1) { const unsigned o = (unsigned)__shfl_xor((int)m, off); m = o > m ? o : m; }
;                 if (k0 == m) k0 = 0u; if (k1 == m) k1 = 0u;
;                 if (lane == 0) selq[tt * 16 + it] = 127 - (int)(m & 127u);
;             }
;             if (lane == 0) { selq[tt * 16 + 13] = 0; selq[tt * 16 + 14] = cur - 1; selq[tt * 16 + 15] = cur; }
;         }
;     }
;     CBAR();
; #pragma unroll
;     for (int tt = 0; tt < 4; ++tt) { const float gc = GN[(size_t)(b * SEQ + t0 + tt) * 48 + (g * 4 + q4) * 3];
;         bf16_t* op = ONSA + (size_t)(b * SEQ + t0 + tt) * 1024 + (g * 4 + q4) * 64 + r16;
; #pragma unroll
;         for (int nt = 0; nt < 4; ++nt) op[nt * 16] = tobf(gc * oc[nt][tt]); }
.Lcmp_tail_q0p2:
	s_add_i32 s75, s75, 1
	s_cmp_eq_u32 s75, 3
	s_cselect_b32 s75, 0, s75
	s_add_i32 s57, s57, 1
	s_cmp_lt_i32 s57, s74
	s_waitcnt vmcnt(2) lgkmcnt(0)
	s_barrier
	s_cbranch_scc1 .Lcmp_top_q0p2
	s_waitcnt lgkmcnt(0)
	s_nop 7
	s_nop 3
	v_and_b32_e32 v232, 15, v184
	v_lshrrev_b32_e32 v233, 4, v184
	v_and_b32_e32 v234, 3, v232
	v_lshrrev_b32_e32 v235, 2, v232
	s_add_i32 s0, s47, s97
	v_add_u32_e32 v253, s0, v234
	s_and_b32 s1, s88, 3
	s_lshl_b32 s1, s1, 2
	v_add_u32_e32 v0, s1, v235
	v_lshlrev_b32_e32 v98, 7, v0
	v_lshl_add_u32 v98, v253, 11, v98
	v_lshl_add_u32 v98, v233, 3, v98
	s_add_u32 s14, s30, 0xf900000
	s_addc_u32 s15, s31, 0
	s_waitcnt vmcnt(0)
	v_mul_f32_e32 v2, v2, v227
	v_mul_f32_e32 v3, v3, v227
	v_mul_f32_e32 v4, v4, v227
	v_mul_f32_e32 v5, v5, v227
	v_mul_f32_e32 v6, v6, v227
	v_mul_f32_e32 v7, v7, v227
	v_mul_f32_e32 v8, v8, v227
	v_mul_f32_e32 v9, v9, v227
	v_mul_f32_e32 v10, v10, v227
	v_mul_f32_e32 v11, v11, v227
	v_mul_f32_e32 v12, v12, v227
	v_mul_f32_e32 v13, v13, v227
	v_mul_f32_e32 v14, v14, v227
	v_mul_f32_e32 v15, v15, v227
	v_mul_f32_e32 v16, v16, v227
	v_mul_f32_e32 v17, v17, v227
	v_cvt_pk_bf16_f32 v216, v2, v3
	v_cvt_pk_bf16_f32 v217, v4, v5
	v_cvt_pk_bf16_f32 v218, v6, v7
	v_cvt_pk_bf16_f32 v219, v8, v9
	v_cvt_pk_bf16_f32 v220, v10, v11
	v_cvt_pk_bf16_f32 v221, v12, v13
	v_cvt_pk_bf16_f32 v222, v14, v15
	v_cvt_pk_bf16_f32 v223, v16, v17
	global_store_dwordx2 v98, v[216:217], s[14:15] offset:0
	global_store_dwordx2 v98, v[218:219], s[14:15] offset:32
	global_store_dwordx2 v98, v[220:221], s[14:15] offset:64
	global_store_dwordx2 v98, v[222:223], s[14:15] offset:96
	s_waitcnt lgkmcnt(0)
	s_cmp_gt_i32 s18, 15
	s_cbranch_scc0 .Ltopk_small_q0
	s_lshl_b32 s19, s80, 10
	s_add_i32 s19, s19, 56384
	v_lshlrev_b32_e32 v96, 4, v184
	v_add_u32_e32 v96, s19, v96
	v_add_u32_e32 v97, 0xfffffffc, v96
	v_sub_u32_e32 v94, 127, v184
	v_sub_u32_e32 v95, 63, v184
	s_mov_b32 s54, 0xffffff80
	s_add_i32 s21, s18, -2
	v_add_u32_e32 v236, 64, v184
	ds_read_b32 v86, v97 offset:0
	ds_read_b128 v[50:53], v96 offset:0
	ds_read_b32 v87, v97 offset:1024
	ds_read_b128 v[54:57], v96 offset:1024
	ds_read_b32 v88, v97 offset:2048
	ds_read_b128 v[58:61], v96 offset:2048
	ds_read_b32 v89, v97 offset:3072
	ds_read_b128 v[62:65], v96 offset:3072
	s_waitcnt lgkmcnt(6)
	v_add_f32_e32 v86, v86, v50
	v_add_f32_e32 v86, v86, v51
	v_add_f32_e32 v86, v86, v52
	v_add_f32_e32 v86, v86, v53
	v_and_or_b32 v18, v86, s54, v94
	s_waitcnt lgkmcnt(4)
	v_add_f32_e32 v87, v87, v54
	v_add_f32_e32 v87, v87, v55
	v_add_f32_e32 v87, v87, v56
	v_add_f32_e32 v87, v87, v57
	v_and_or_b32 v22, v87, s54, v95
	s_waitcnt lgkmcnt(2)
	v_add_f32_e32 v88, v88, v58
	v_add_f32_e32 v88, v88, v59
	v_add_f32_e32 v88, v88, v60
	v_add_f32_e32 v88, v88, v61
	v_and_or_b32 v19, v88, s54, v94
	s_waitcnt lgkmcnt(0)
	v_add_f32_e32 v89, v89, v62
	v_add_f32_e32 v89, v89, v63
	v_add_f32_e32 v89, v89, v64
	v_add_f32_e32 v89, v89, v65
	v_and_or_b32 v23, v89, s54, v95
	ds_read_b32 v90, v97 offset:4096
	ds_read_b128 v[66:69], v96 offset:4096
	ds_read_b32 v91, v97 offset:5120
	ds_read_b128 v[70:73], v96 offset:5120
	ds_read_b32 v92, v97 offset:6144
	ds_read_b128 v[74:77], v96 offset:6144
	ds_read_b32 v93, v97 offset:7168
	ds_read_b128 v[78:81], v96 offset:7168
	s_waitcnt lgkmcnt(6)
	v_add_f32_e32 v90, v90, v66
	v_add_f32_e32 v90, v90, v67
	v_add_f32_e32 v90, v90, v68
	v_add_f32_e32 v90, v90, v69
	v_and_or_b32 v20, v90, s54, v94
	s_waitcnt lgkmcnt(4)
	v_add_f32_e32 v91, v91, v70
	v_add_f32_e32 v91, v91, v71
	v_add_f32_e32 v91, v91, v72
	v_add_f32_e32 v91, v91, v73
	v_and_or_b32 v24, v91, s54, v95
	s_waitcnt lgkmcnt(2)
	v_add_f32_e32 v92, v92, v74
	v_add_f32_e32 v92, v92, v75
	v_add_f32_e32 v92, v92, v76
	v_add_f32_e32 v92, v92, v77
	v_and_or_b32 v21, v92, s54, v94
	s_waitcnt lgkmcnt(0)
	v_add_f32_e32 v93, v93, v78
	v_add_f32_e32 v93, v93, v79
	v_add_f32_e32 v93, v93, v80
	v_add_f32_e32 v93, v93, v81
	v_and_or_b32 v25, v93, s54, v95
	v_cmp_le_i32_e64 s[14:15], v184, s21
	v_cmp_lt_i32_e64 s[34:35], 0, v184
	s_nop 0
	s_and_b64 s[14:15], s[14:15], s[34:35]
	v_cmp_le_i32_e64 s[34:35], v236, s21
	v_cndmask_b32_e64 v18, 0, v18, s[14:15]
	s_nop 0
	v_cndmask_b32_e64 v22, 0, v22, s[34:35]
	v_mov_b32_e32 v82, 127
	v_cndmask_b32_e64 v19, 0, v19, s[14:15]
	v_cndmask_b32_e64 v23, 0, v23, s[34:35]
	v_mov_b32_e32 v83, 127
	v_cndmask_b32_e64 v20, 0, v20, s[14:15]
	v_cndmask_b32_e64 v24, 0, v24, s[34:35]
	v_mov_b32_e32 v84, 127
	v_cndmask_b32_e64 v21, 0, v21, s[14:15]
	v_cndmask_b32_e64 v25, 0, v25, s[34:35]
	v_mov_b32_e32 v85, 127
	v_max_u32_e32 v26, v18, v22
	v_max_u32_e32 v27, v19, v23
	v_max_u32_e32 v28, v20, v24
	v_max_u32_e32 v29, v21, v25
	v_max_u32_dpp v26, v26, v26 quad_perm:[1,0,3,2] row_mask:0xf bank_mask:0xf
	v_max_u32_dpp v27, v27, v27 quad_perm:[1,0,3,2] row_mask:0xf bank_mask:0xf
	v_max_u32_dpp v28, v28, v28 quad_perm:[1,0,3,2] row_mask:0xf bank_mask:0xf
	v_max_u32_dpp v29, v29, v29 quad_perm:[1,0,3,2] row_mask:0xf bank_mask:0xf
	v_max_u32_dpp v26, v26, v26 quad_perm:[2,3,0,1] row_mask:0xf bank_mask:0xf
	v_max_u32_dpp v27, v27, v27 quad_perm:[2,3,0,1] row_mask:0xf bank_mask:0xf
	v_max_u32_dpp v28, v28, v28 quad_perm:[2,3,0,1] row_mask:0xf bank_mask:0xf
	v_max_u32_dpp v29, v29, v29 quad_perm:[2,3,0,1] row_mask:0xf bank_mask:0xf
	v_max_u32_dpp v26, v26, v26 row_half_mirror row_mask:0xf bank_mask:0xf
	v_max_u32_dpp v27, v27, v27 row_half_mirror row_mask:0xf bank_mask:0xf
	v_max_u32_dpp v28, v28, v28 row_half_mirror row_mask:0xf bank_mask:0xf
	v_max_u32_dpp v29, v29, v29 row_half_mirror row_mask:0xf bank_mask:0xf
	v_max_u32_dpp v26, v26, v26 row_mirror row_mask:0xf bank_mask:0xf
; __device__ __forceinline__ void nsa_quad_pre(int bg, int quad, const bf16_t* Q, const bf16_t* KV, const bf16_t* KCMP, const bf16_t* VCMPT, const float* GN, bf16_t* ONSA, ...
;     ...
;             for (int it = 0; it < 13; ++it) {
;                 unsigned m = k0 > k1 ? k0 : k1;
; #pragma unroll
;                 for (int off = 32; off >= 1; off >>= 1) { const unsigned o = (unsigned)__shfl_xor((int)m, off); m = o > m ? o : m; }
;                 if (k0 == m) k0 = 0u; if (k1 == m) k1 = 0u;
;                 if (lane == 0) selq[tt * 16 + it] = 127 - (int)(m & 127u);
	v_max_u32_dpp v27, v27, v27 row_mirror row_mask:0xf bank_mask:0xf
	v_max_u32_dpp v28, v28, v28 row_mirror row_mask:0xf bank_mask:0xf
	v_max_u32_dpp v29, v29, v29 row_mirror row_mask:0xf bank_mask:0xf
	v_max_u32_dpp v26, v26, v26 row_bcast:15 row_mask:0xa bank_mask:0xf
	v_max_u32_dpp v27, v27, v27 row_bcast:15 row_mask:0xa bank_mask:0xf
	v_max_u32_dpp v28, v28, v28 row_bcast:15 row_mask:0xa bank_mask:0xf
	v_max_u32_dpp v29, v29, v29 row_bcast:15 row_mask:0xa bank_mask:0xf
	v_max_u32_dpp v26, v26, v26 row_bcast:31 row_mask:0xc bank_mask:0xf
	v_max_u32_dpp v27, v27, v27 row_bcast:31 row_mask:0xc bank_mask:0xf
	v_max_u32_dpp v28, v28, v28 row_bcast:31 row_mask:0xc bank_mask:0xf
	v_max_u32_dpp v29, v29, v29 row_bcast:31 row_mask:0xc bank_mask:0xf
	v_readlane_b32 s14, v26, 63
	v_readlane_b32 s15, v27, 63
	v_readlane_b32 s34, v28, 63
	v_readlane_b32 s35, v29, 63
	v_writelane_b32 v82, s14, 0
	v_writelane_b32 v83, s15, 0
	v_writelane_b32 v84, s34, 0
	v_writelane_b32 v85, s35, 0
	v_cmp_ne_u32_e64 s[42:43], s14, v18
	v_cmp_ne_u32_e64 s[66:67], s14, v22
	v_cmp_ne_u32_e64 s[0:1], s15, v19
	v_cmp_ne_u32_e32 vcc, s15, v23
	v_cndmask_b32_e64 v18, 0, v18, s[42:43]
	v_cndmask_b32_e64 v22, 0, v22, s[66:67]
	v_cndmask_b32_e64 v19, 0, v19, s[0:1]
	v_cndmask_b32_e32 v23, 0, v23, vcc
	v_cmp_ne_u32_e64 s[42:43], s34, v20
	v_cmp_ne_u32_e64 s[66:67], s34, v24
	v_cmp_ne_u32_e64 s[0:1], s35, v21
	v_cmp_ne_u32_e32 vcc, s35, v25
	v_cndmask_b32_e64 v20, 0, v20, s[42:43]
	v_cndmask_b32_e64 v24, 0, v24, s[66:67]
	v_cndmask_b32_e64 v21, 0, v21, s[0:1]
	v_cndmask_b32_e32 v25, 0, v25, vcc
	v_max_u32_e32 v26, v18, v22
	v_max_u32_e32 v27, v19, v23
	v_max_u32_e32 v28, v20, v24
	v_max_u32_e32 v29, v21, v25
	v_max_u32_dpp v26, v26, v26 quad_perm:[1,0,3,2] row_mask:0xf bank_mask:0xf
	v_max_u32_dpp v27, v27, v27 quad_perm:[1,0,3,2] row_mask:0xf bank_mask:0xf
	v_max_u32_dpp v28, v28, v28 quad_perm:[1,0,3,2] row_mask:0xf bank_mask:0xf
	v_max_u32_dpp v29, v29, v29 quad_perm:[1,0,3,2] row_mask:0xf bank_mask:0xf
	v_max_u32_dpp v26, v26, v26 quad_perm:[2,3,0,1] row_mask:0xf bank_mask:0xf
	v_max_u32_dpp v27, v27, v27 quad_perm:[2,3,0,1] row_mask:0xf bank_mask:0xf
	v_max_u32_dpp v28, v28, v28 quad_perm:[2,3,0,1] row_mask:0xf bank_mask:0xf
	v_max_u32_dpp v29, v29, v29 quad_perm:[2,3,0,1] row_mask:0xf bank_mask:0xf
	v_max_u32_dpp v26, v26, v26 row_half_mirror row_mask:0xf bank_mask:0xf
	v_max_u32_dpp v27, v27, v27 row_half_mirror row_mask:0xf bank_mask:0xf
	v_max_u32_dpp v28, v28, v28 row_half_mirror row_mask:0xf bank_mask:0xf
	v_max_u32_dpp v29, v29, v29 row_half_mirror row_mask:0xf bank_mask:0xf
	v_max_u32_dpp v26, v26, v26 row_mirror row_mask:0xf bank_mask:0xf
	v_max_u32_dpp v27, v27, v27 row_mirror row_mask:0xf bank_mask:0xf
	v_max_u32_dpp v28, v28, v28 row_mirror row_mask:0xf bank_mask:0xf
	v_max_u32_dpp v29, v29, v29 row_mirror row_mask:0xf bank_mask:0xf
	v_max_u32_dpp v26, v26, v26 row_bcast:15 row_mask:0xa bank_mask:0xf
	v_max_u32_dpp v27, v27, v27 row_bcast:15 row_mask:0xa bank_mask:0xf
	v_max_u32_dpp v28, v28, v28 row_bcast:15 row_mask:0xa bank_mask:0xf
	v_max_u32_dpp v29, v29, v29 row_bcast:15 row_mask:0xa bank_mask:0xf
	v_max_u32_dpp v26, v26, v26 row_bcast:31 row_mask:0xc bank_mask:0xf
	v_max_u32_dpp v27, v27, v27 row_bcast:31 row_mask:0xc bank_mask:0xf
	v_max_u32_dpp v28, v28, v28 row_bcast:31 row_mask:0xc bank_mask:0xf
	v_max_u32_dpp v29, v29, v29 row_bcast:31 row_mask:0xc bank_mask:0xf
	v_readlane_b32 s14, v26, 63
	v_readlane_b32 s15, v27, 63
	v_readlane_b32 s34, v28, 63
	v_readlane_b32 s35, v29, 63
	v_writelane_b32 v82, s14, 1
	v_writelane_b32 v83, s15, 1
	v_writelane_b32 v84, s34, 1
	v_writelane_b32 v85, s35, 1
	v_cmp_ne_u32_e64 s[42:43], s14, v18
	v_cmp_ne_u32_e64 s[66:67], s14, v22
	v_cmp_ne_u32_e64 s[0:1], s15, v19
	v_cmp_ne_u32_e32 vcc, s15, v23
	v_cndmask_b32_e64 v18, 0, v18, s[42:43]
	v_cndmask_b32_e64 v22, 0, v22, s[66:67]
	v_cndmask_b32_e64 v19, 0, v19, s[0:1]
	v_cndmask_b32_e32 v23, 0, v23, vcc
	v_cmp_ne_u32_e64 s[42:43], s34, v20
	v_cmp_ne_u32_e64 s[66:67], s34, v24
	v_cmp_ne_u32_e64 s[0:1], s35, v21
	v_cmp_ne_u32_e32 vcc, s35, v25
	v_cndmask_b32_e64 v20, 0, v20, s[42:43]
	v_cndmask_b32_e64 v24, 0, v24, s[66:67]
	v_cndmask_b32_e64 v21, 0, v21, s[0:1]
	v_cndmask_b32_e32 v25, 0, v25, vcc
	v_max_u32_e32 v26, v18, v22
	v_max_u32_e32 v27, v19, v23
	v_max_u32_e32 v28, v20, v24
	v_max_u32_e32 v29, v21, v25
	v_max_u32_dpp v26, v26, v26 quad_perm:[1,0,3,2] row_mask:0xf bank_mask:0xf
	v_max_u32_dpp v27, v27, v27 quad_perm:[1,0,3,2] row_mask:0xf bank_mask:0xf
	v_max_u32_dpp v28, v28, v28 quad_perm:[1,0,3,2] row_mask:0xf bank_mask:0xf
	v_max_u32_dpp v29, v29, v29 quad_perm:[1,0,3,2] row_mask:0xf bank_mask:0xf
	v_max_u32_dpp v26, v26, v26 quad_perm:[2,3,0,1] row_mask:0xf bank_mask:0xf
	v_max_u32_dpp v27, v27, v27 quad_perm:[2,3,0,1] row_mask:0xf bank_mask:0xf
	v_max_u32_dpp v28, v28, v28 quad_perm:[2,3,0,1] row_mask:0xf bank_mask:0xf
	v_max_u32_dpp v29, v29, v29 quad_perm:[2,3,0,1] row_mask:0xf bank_mask:0xf
	v_max_u32_dpp v26, v26, v26 row_half_mirror row_mask:0xf bank_mask:0xf
	v_max_u32_dpp v27, v27, v27 row_half_mirror row_mask:0xf bank_mask:0xf
	v_max_u32_dpp v28, v28, v28 row_half_mirror row_mask:0xf bank_mask:0xf
	v_max_u32_dpp v29, v29, v29 row_half_mirror row_mask:0xf bank_mask:0xf
	v_max_u32_dpp v26, v26, v26 row_mirror row_mask:0xf bank_mask:0xf
	v_max_u32_dpp v27, v27, v27 row_mirror row_mask:0xf bank_mask:0xf
	v_max_u32_dpp v28, v28, v28 row_mirror row_mask:0xf bank_mask:0xf
	v_max_u32_dpp v29, v29, v29 row_mirror row_mask:0xf bank_mask:0xf
	v_max_u32_dpp v26, v26, v26 row_bcast:15 row_mask:0xa bank_mask:0xf
	v_max_u32_dpp v27, v27, v27 row_bcast:15 row_mask:0xa bank_mask:0xf
; __device__ __forceinline__ void nsa_quad_pre(int bg, int quad, const bf16_t* Q, const bf16_t* KV, const bf16_t* KCMP, const bf16_t* VCMPT, const float* GN, bf16_t* ONSA, ...
;     ...
;             for (int it = 0; it < 13; ++it) {
;                 unsigned m = k0 > k1 ? k0 : k1;
; #pragma unroll
;                 for (int off = 32; off >= 1; off >>= 1) { const unsigned o = (unsigned)__shfl_xor((int)m, off); m = o > m ? o : m; }
;                 if (k0 == m) k0 = 0u; if (k1 == m) k1 = 0u;
;                 if (lane == 0) selq[tt * 16 + it] = 127 - (int)(m & 127u);
	v_max_u32_dpp v28, v28, v28 row_bcast:15 row_mask:0xa bank_mask:0xf
	v_max_u32_dpp v29, v29, v29 row_bcast:15 row_mask:0xa bank_mask:0xf
	v_max_u32_dpp v26, v26, v26 row_bcast:31 row_mask:0xc bank_mask:0xf
	v_max_u32_dpp v27, v27, v27 row_bcast:31 row_mask:0xc bank_mask:0xf
	v_max_u32_dpp v28, v28, v28 row_bcast:31 row_mask:0xc bank_mask:0xf
	v_max_u32_dpp v29, v29, v29 row_bcast:31 row_mask:0xc bank_mask:0xf
	v_readlane_b32 s14, v26, 63
	v_readlane_b32 s15, v27, 63
	v_readlane_b32 s34, v28, 63
	v_readlane_b32 s35, v29, 63
	v_writelane_b32 v82, s14, 2
	v_writelane_b32 v83, s15, 2
	v_writelane_b32 v84, s34, 2
	v_writelane_b32 v85, s35, 2
	v_cmp_ne_u32_e64 s[42:43], s14, v18
	v_cmp_ne_u32_e64 s[66:67], s14, v22
	v_cmp_ne_u32_e64 s[0:1], s15, v19
	v_cmp_ne_u32_e32 vcc, s15, v23
	v_cndmask_b32_e64 v18, 0, v18, s[42:43]
	v_cndmask_b32_e64 v22, 0, v22, s[66:67]
	v_cndmask_b32_e64 v19, 0, v19, s[0:1]
	v_cndmask_b32_e32 v23, 0, v23, vcc
	v_cmp_ne_u32_e64 s[42:43], s34, v20
	v_cmp_ne_u32_e64 s[66:67], s34, v24
	v_cmp_ne_u32_e64 s[0:1], s35, v21
	v_cmp_ne_u32_e32 vcc, s35, v25
	v_cndmask_b32_e64 v20, 0, v20, s[42:43]
	v_cndmask_b32_e64 v24, 0, v24, s[66:67]
	v_cndmask_b32_e64 v21, 0, v21, s[0:1]
	v_cndmask_b32_e32 v25, 0, v25, vcc
	v_max_u32_e32 v26, v18, v22
	v_max_u32_e32 v27, v19, v23
	v_max_u32_e32 v28, v20, v24
	v_max_u32_e32 v29, v21, v25
	v_max_u32_dpp v26, v26, v26 quad_perm:[1,0,3,2] row_mask:0xf bank_mask:0xf
	v_max_u32_dpp v27, v27, v27 quad_perm:[1,0,3,2] row_mask:0xf bank_mask:0xf
	v_max_u32_dpp v28, v28, v28 quad_perm:[1,0,3,2] row_mask:0xf bank_mask:0xf
	v_max_u32_dpp v29, v29, v29 quad_perm:[1,0,3,2] row_mask:0xf bank_mask:0xf
	v_max_u32_dpp v26, v26, v26 quad_perm:[2,3,0,1] row_mask:0xf bank_mask:0xf
	v_max_u32_dpp v27, v27, v27 quad_perm:[2,3,0,1] row_mask:0xf bank_mask:0xf
	v_max_u32_dpp v28, v28, v28 quad_perm:[2,3,0,1] row_mask:0xf bank_mask:0xf
	v_max_u32_dpp v29, v29, v29 quad_perm:[2,3,0,1] row_mask:0xf bank_mask:0xf
	v_max_u32_dpp v26, v26, v26 row_half_mirror row_mask:0xf bank_mask:0xf
	v_max_u32_dpp v27, v27, v27 row_half_mirror row_mask:0xf bank_mask:0xf
	v_max_u32_dpp v28, v28, v28 row_half_mirror row_mask:0xf bank_mask:0xf
	v_max_u32_dpp v29, v29, v29 row_half_mirror row_mask:0xf bank_mask:0xf
	v_max_u32_dpp v26, v26, v26 row_mirror row_mask:0xf bank_mask:0xf
	v_max_u32_dpp v27, v27, v27 row_mirror row_mask:0xf bank_mask:0xf
	v_max_u32_dpp v28, v28, v28 row_mirror row_mask:0xf bank_mask:0xf
	v_max_u32_dpp v29, v29, v29 row_mirror row_mask:0xf bank_mask:0xf
	v_max_u32_dpp v26, v26, v26 row_bcast:15 row_mask:0xa bank_mask:0xf
	v_max_u32_dpp v27, v27, v27 row_bcast:15 row_mask:0xa bank_mask:0xf
	v_max_u32_dpp v28, v28, v28 row_bcast:15 row_mask:0xa bank_mask:0xf
	v_max_u32_dpp v29, v29, v29 row_bcast:15 row_mask:0xa bank_mask:0xf
	v_max_u32_dpp v26, v26, v26 row_bcast:31 row_mask:0xc bank_mask:0xf
	v_max_u32_dpp v27, v27, v27 row_bcast:31 row_mask:0xc bank_mask:0xf
	v_max_u32_dpp v28, v28, v28 row_bcast:31 row_mask:0xc bank_mask:0xf
	v_max_u32_dpp v29, v29, v29 row_bcast:31 row_mask:0xc bank_mask:0xf
	v_readlane_b32 s14, v26, 63
	v_readlane_b32 s15, v27, 63
	v_readlane_b32 s34, v28, 63
	v_readlane_b32 s35, v29, 63
	v_writelane_b32 v82, s14, 3
	v_writelane_b32 v83, s15, 3
	v_writelane_b32 v84, s34, 3
	v_writelane_b32 v85, s35, 3
	v_cmp_ne_u32_e64 s[42:43], s14, v18
	v_cmp_ne_u32_e64 s[66:67], s14, v22
	v_cmp_ne_u32_e64 s[0:1], s15, v19
	v_cmp_ne_u32_e32 vcc, s15, v23
	v_cndmask_b32_e64 v18, 0, v18, s[42:43]
	v_cndmask_b32_e64 v22, 0, v22, s[66:67]
	v_cndmask_b32_e64 v19, 0, v19, s[0:1]
	v_cndmask_b32_e32 v23, 0, v23, vcc
	v_cmp_ne_u32_e64 s[42:43], s34, v20
	v_cmp_ne_u32_e64 s[66:67], s34, v24
	v_cmp_ne_u32_e64 s[0:1], s35, v21
	v_cmp_ne_u32_e32 vcc, s35, v25
	v_cndmask_b32_e64 v20, 0, v20, s[42:43]
	v_cndmask_b32_e64 v24, 0, v24, s[66:67]
	v_cndmask_b32_e64 v21, 0, v21, s[0:1]
	v_cndmask_b32_e32 v25, 0, v25, vcc
	v_max_u32_e32 v26, v18, v22
	v_max_u32_e32 v27, v19, v23
	v_max_u32_e32 v28, v20, v24
	v_max_u32_e32 v29, v21, v25
	v_max_u32_dpp v26, v26, v26 quad_perm:[1,0,3,2] row_mask:0xf bank_mask:0xf
	v_max_u32_dpp v27, v27, v27 quad_perm:[1,0,3,2] row_mask:0xf bank_mask:0xf
	v_max_u32_dpp v28, v28, v28 quad_perm:[1,0,3,2] row_mask:0xf bank_mask:0xf
	v_max_u32_dpp v29, v29, v29 quad_perm:[1,0,3,2] row_mask:0xf bank_mask:0xf
	v_max_u32_dpp v26, v26, v26 quad_perm:[2,3,0,1] row_mask:0xf bank_mask:0xf
	v_max_u32_dpp v27, v27, v27 quad_perm:[2,3,0,1] row_mask:0xf bank_mask:0xf
	v_max_u32_dpp v28, v28, v28 quad_perm:[2,3,0,1] row_mask:0xf bank_mask:0xf
	v_max_u32_dpp v29, v29, v29 quad_perm:[2,3,0,1] row_mask:0xf bank_mask:0xf
	v_max_u32_dpp v26, v26, v26 row_half_mirror row_mask:0xf bank_mask:0xf
	v_max_u32_dpp v27, v27, v27 row_half_mirror row_mask:0xf bank_mask:0xf
	v_max_u32_dpp v28, v28, v28 row_half_mirror row_mask:0xf bank_mask:0xf
	v_max_u32_dpp v29, v29, v29 row_half_mirror row_mask:0xf bank_mask:0xf
	v_max_u32_dpp v26, v26, v26 row_mirror row_mask:0xf bank_mask:0xf
	v_max_u32_dpp v27, v27, v27 row_mirror row_mask:0xf bank_mask:0xf
	v_max_u32_dpp v28, v28, v28 row_mirror row_mask:0xf bank_mask:0xf
	v_max_u32_dpp v29, v29, v29 row_mirror row_mask:0xf bank_mask:0xf
	v_max_u32_dpp v26, v26, v26 row_bcast:15 row_mask:0xa bank_mask:0xf
	v_max_u32_dpp v27, v27, v27 row_bcast:15 row_mask:0xa bank_mask:0xf
	v_max_u32_dpp v28, v28, v28 row_bcast:15 row_mask:0xa bank_mask:0xf
	v_max_u32_dpp v29, v29, v29 row_bcast:15 row_mask:0xa bank_mask:0xf
	v_max_u32_dpp v26, v26, v26 row_bcast:31 row_mask:0xc bank_mask:0xf
	v_max_u32_dpp v27, v27, v27 row_bcast:31 row_mask:0xc bank_mask:0xf
	v_max_u32_dpp v28, v28, v28 row_bcast:31 row_mask:0xc bank_mask:0xf
; __device__ __forceinline__ void nsa_quad_pre(int bg, int quad, const bf16_t* Q, const bf16_t* KV, const bf16_t* KCMP, const bf16_t* VCMPT, const float* GN, bf16_t* ONSA, ...
;     ...
;             for (int it = 0; it < 13; ++it) {
;                 unsigned m = k0 > k1 ? k0 : k1;
; #pragma unroll
;                 for (int off = 32; off >= 1; off >>= 1) { const unsigned o = (unsigned)__shfl_xor((int)m, off); m = o > m ? o : m; }
;                 if (k0 == m) k0 = 0u; if (k1 == m) k1 = 0u;
;                 if (lane == 0) selq[tt * 16 + it] = 127 - (int)(m & 127u);
	v_max_u32_dpp v29, v29, v29 row_bcast:31 row_mask:0xc bank_mask:0xf
	v_readlane_b32 s14, v26, 63
	v_readlane_b32 s15, v27, 63
	v_readlane_b32 s34, v28, 63
	v_readlane_b32 s35, v29, 63
	v_writelane_b32 v82, s14, 4
	v_writelane_b32 v83, s15, 4
	v_writelane_b32 v84, s34, 4
	v_writelane_b32 v85, s35, 4
	v_cmp_ne_u32_e64 s[42:43], s14, v18
	v_cmp_ne_u32_e64 s[66:67], s14, v22
	v_cmp_ne_u32_e64 s[0:1], s15, v19
	v_cmp_ne_u32_e32 vcc, s15, v23
	v_cndmask_b32_e64 v18, 0, v18, s[42:43]
	v_cndmask_b32_e64 v22, 0, v22, s[66:67]
	v_cndmask_b32_e64 v19, 0, v19, s[0:1]
	v_cndmask_b32_e32 v23, 0, v23, vcc
	v_cmp_ne_u32_e64 s[42:43], s34, v20
	v_cmp_ne_u32_e64 s[66:67], s34, v24
	v_cmp_ne_u32_e64 s[0:1], s35, v21
	v_cmp_ne_u32_e32 vcc, s35, v25
	v_cndmask_b32_e64 v20, 0, v20, s[42:43]
	v_cndmask_b32_e64 v24, 0, v24, s[66:67]
	v_cndmask_b32_e64 v21, 0, v21, s[0:1]
	v_cndmask_b32_e32 v25, 0, v25, vcc
	v_max_u32_e32 v26, v18, v22
	v_max_u32_e32 v27, v19, v23
	v_max_u32_e32 v28, v20, v24
	v_max_u32_e32 v29, v21, v25
	v_max_u32_dpp v26, v26, v26 quad_perm:[1,0,3,2] row_mask:0xf bank_mask:0xf
	v_max_u32_dpp v27, v27, v27 quad_perm:[1,0,3,2] row_mask:0xf bank_mask:0xf
	v_max_u32_dpp v28, v28, v28 quad_perm:[1,0,3,2] row_mask:0xf bank_mask:0xf
	v_max_u32_dpp v29, v29, v29 quad_perm:[1,0,3,2] row_mask:0xf bank_mask:0xf
	v_max_u32_dpp v26, v26, v26 quad_perm:[2,3,0,1] row_mask:0xf bank_mask:0xf
	v_max_u32_dpp v27, v27, v27 quad_perm:[2,3,0,1] row_mask:0xf bank_mask:0xf
	v_max_u32_dpp v28, v28, v28 quad_perm:[2,3,0,1] row_mask:0xf bank_mask:0xf
	v_max_u32_dpp v29, v29, v29 quad_perm:[2,3,0,1] row_mask:0xf bank_mask:0xf
	v_max_u32_dpp v26, v26, v26 row_half_mirror row_mask:0xf bank_mask:0xf
	v_max_u32_dpp v27, v27, v27 row_half_mirror row_mask:0xf bank_mask:0xf
	v_max_u32_dpp v28, v28, v28 row_half_mirror row_mask:0xf bank_mask:0xf
	v_max_u32_dpp v29, v29, v29 row_half_mirror row_mask:0xf bank_mask:0xf
	v_max_u32_dpp v26, v26, v26 row_mirror row_mask:0xf bank_mask:0xf
	v_max_u32_dpp v27, v27, v27 row_mirror row_mask:0xf bank_mask:0xf
	v_max_u32_dpp v28, v28, v28 row_mirror row_mask:0xf bank_mask:0xf
	v_max_u32_dpp v29, v29, v29 row_mirror row_mask:0xf bank_mask:0xf
	v_max_u32_dpp v26, v26, v26 row_bcast:15 row_mask:0xa bank_mask:0xf
	v_max_u32_dpp v27, v27, v27 row_bcast:15 row_mask:0xa bank_mask:0xf
	v_max_u32_dpp v28, v28, v28 row_bcast:15 row_mask:0xa bank_mask:0xf
	v_max_u32_dpp v29, v29, v29 row_bcast:15 row_mask:0xa bank_mask:0xf
	v_max_u32_dpp v26, v26, v26 row_bcast:31 row_mask:0xc bank_mask:0xf
	v_max_u32_dpp v27, v27, v27 row_bcast:31 row_mask:0xc bank_mask:0xf
	v_max_u32_dpp v28, v28, v28 row_bcast:31 row_mask:0xc bank_mask:0xf
	v_max_u32_dpp v29, v29, v29 row_bcast:31 row_mask:0xc bank_mask:0xf
	v_readlane_b32 s14, v26, 63
	v_readlane_b32 s15, v27, 63
	v_readlane_b32 s34, v28, 63
	v_readlane_b32 s35, v29, 63
	v_writelane_b32 v82, s14, 5
	v_writelane_b32 v83, s15, 5
	v_writelane_b32 v84, s34, 5
	v_writelane_b32 v85, s35, 5
	v_cmp_ne_u32_e64 s[42:43], s14, v18
	v_cmp_ne_u32_e64 s[66:67], s14, v22
	v_cmp_ne_u32_e64 s[0:1], s15, v19
	v_cmp_ne_u32_e32 vcc, s15, v23
	v_cndmask_b32_e64 v18, 0, v18, s[42:43]
	v_cndmask_b32_e64 v22, 0, v22, s[66:67]
	v_cndmask_b32_e64 v19, 0, v19, s[0:1]
	v_cndmask_b32_e32 v23, 0, v23, vcc
	v_cmp_ne_u32_e64 s[42:43], s34, v20
	v_cmp_ne_u32_e64 s[66:67], s34, v24
	v_cmp_ne_u32_e64 s[0:1], s35, v21
	v_cmp_ne_u32_e32 vcc, s35, v25
	v_cndmask_b32_e64 v20, 0, v20, s[42:43]
	v_cndmask_b32_e64 v24, 0, v24, s[66:67]
	v_cndmask_b32_e64 v21, 0, v21, s[0:1]
	v_cndmask_b32_e32 v25, 0, v25, vcc
	v_max_u32_e32 v26, v18, v22
	v_max_u32_e32 v27, v19, v23
	v_max_u32_e32 v28, v20, v24
	v_max_u32_e32 v29, v21, v25
	v_max_u32_dpp v26, v26, v26 quad_perm:[1,0,3,2] row_mask:0xf bank_mask:0xf
	v_max_u32_dpp v27, v27, v27 quad_perm:[1,0,3,2] row_mask:0xf bank_mask:0xf
	v_max_u32_dpp v28, v28, v28 quad_perm:[1,0,3,2] row_mask:0xf bank_mask:0xf
	v_max_u32_dpp v29, v29, v29 quad_perm:[1,0,3,2] row_mask:0xf bank_mask:0xf
	v_max_u32_dpp v26, v26, v26 quad_perm:[2,3,0,1] row_mask:0xf bank_mask:0xf
	v_max_u32_dpp v27, v27, v27 quad_perm:[2,3,0,1] row_mask:0xf bank_mask:0xf
	v_max_u32_dpp v28, v28, v28 quad_perm:[2,3,0,1] row_mask:0xf bank_mask:0xf
	v_max_u32_dpp v29, v29, v29 quad_perm:[2,3,0,1] row_mask:0xf bank_mask:0xf
	v_max_u32_dpp v26, v26, v26 row_half_mirror row_mask:0xf bank_mask:0xf
	v_max_u32_dpp v27, v27, v27 row_half_mirror row_mask:0xf bank_mask:0xf
	v_max_u32_dpp v28, v28, v28 row_half_mirror row_mask:0xf bank_mask:0xf
	v_max_u32_dpp v29, v29, v29 row_half_mirror row_mask:0xf bank_mask:0xf
	v_max_u32_dpp v26, v26, v26 row_mirror row_mask:0xf bank_mask:0xf
	v_max_u32_dpp v27, v27, v27 row_mirror row_mask:0xf bank_mask:0xf
	v_max_u32_dpp v28, v28, v28 row_mirror row_mask:0xf bank_mask:0xf
	v_max_u32_dpp v29, v29, v29 row_mirror row_mask:0xf bank_mask:0xf
	v_max_u32_dpp v26, v26, v26 row_bcast:15 row_mask:0xa bank_mask:0xf
	v_max_u32_dpp v27, v27, v27 row_bcast:15 row_mask:0xa bank_mask:0xf
	v_max_u32_dpp v28, v28, v28 row_bcast:15 row_mask:0xa bank_mask:0xf
	v_max_u32_dpp v29, v29, v29 row_bcast:15 row_mask:0xa bank_mask:0xf
	v_max_u32_dpp v26, v26, v26 row_bcast:31 row_mask:0xc bank_mask:0xf
	v_max_u32_dpp v27, v27, v27 row_bcast:31 row_mask:0xc bank_mask:0xf
	v_max_u32_dpp v28, v28, v28 row_bcast:31 row_mask:0xc bank_mask:0xf
	v_max_u32_dpp v29, v29, v29 row_bcast:31 row_mask:0xc bank_mask:0xf
	v_readlane_b32 s14, v26, 63
	v_readlane_b32 s15, v27, 63
	v_readlane_b32 s34, v28, 63
	v_readlane_b32 s35, v29, 63
	v_writelane_b32 v82, s14, 6
	v_writelane_b32 v83, s15, 6
	v_writelane_b32 v84, s34, 6
	v_writelane_b32 v85, s35, 6
	v_cmp_ne_u32_e64 s[42:43], s14, v18
; __device__ __forceinline__ void nsa_quad_pre(int bg, int quad, const bf16_t* Q, const bf16_t* KV, const bf16_t* KCMP, const bf16_t* VCMPT, const float* GN, bf16_t* ONSA, ...
;     ...
;             for (int it = 0; it < 13; ++it) {
;                 unsigned m = k0 > k1 ? k0 : k1;
; #pragma unroll
;                 for (int off = 32; off >= 1; off >>= 1) { const unsigned o = (unsigned)__shfl_xor((int)m, off); m = o > m ? o : m; }
;                 if (k0 == m) k0 = 0u; if (k1 == m) k1 = 0u;
;                 if (lane == 0) selq[tt * 16 + it] = 127 - (int)(m & 127u);
	v_cmp_ne_u32_e64 s[66:67], s14, v22
	v_cmp_ne_u32_e64 s[0:1], s15, v19
	v_cmp_ne_u32_e32 vcc, s15, v23
	v_cndmask_b32_e64 v18, 0, v18, s[42:43]
	v_cndmask_b32_e64 v22, 0, v22, s[66:67]
	v_cndmask_b32_e64 v19, 0, v19, s[0:1]
	v_cndmask_b32_e32 v23, 0, v23, vcc
	v_cmp_ne_u32_e64 s[42:43], s34, v20
	v_cmp_ne_u32_e64 s[66:67], s34, v24
	v_cmp_ne_u32_e64 s[0:1], s35, v21
	v_cmp_ne_u32_e32 vcc, s35, v25
	v_cndmask_b32_e64 v20, 0, v20, s[42:43]
	v_cndmask_b32_e64 v24, 0, v24, s[66:67]
	v_cndmask_b32_e64 v21, 0, v21, s[0:1]
	v_cndmask_b32_e32 v25, 0, v25, vcc
	v_max_u32_e32 v26, v18, v22
	v_max_u32_e32 v27, v19, v23
	v_max_u32_e32 v28, v20, v24
	v_max_u32_e32 v29, v21, v25
	v_max_u32_dpp v26, v26, v26 quad_perm:[1,0,3,2] row_mask:0xf bank_mask:0xf
	v_max_u32_dpp v27, v27, v27 quad_perm:[1,0,3,2] row_mask:0xf bank_mask:0xf
	v_max_u32_dpp v28, v28, v28 quad_perm:[1,0,3,2] row_mask:0xf bank_mask:0xf
	v_max_u32_dpp v29, v29, v29 quad_perm:[1,0,3,2] row_mask:0xf bank_mask:0xf
	v_max_u32_dpp v26, v26, v26 quad_perm:[2,3,0,1] row_mask:0xf bank_mask:0xf
	v_max_u32_dpp v27, v27, v27 quad_perm:[2,3,0,1] row_mask:0xf bank_mask:0xf
	v_max_u32_dpp v28, v28, v28 quad_perm:[2,3,0,1] row_mask:0xf bank_mask:0xf
	v_max_u32_dpp v29, v29, v29 quad_perm:[2,3,0,1] row_mask:0xf bank_mask:0xf
	v_max_u32_dpp v26, v26, v26 row_half_mirror row_mask:0xf bank_mask:0xf
	v_max_u32_dpp v27, v27, v27 row_half_mirror row_mask:0xf bank_mask:0xf
	v_max_u32_dpp v28, v28, v28 row_half_mirror row_mask:0xf bank_mask:0xf
	v_max_u32_dpp v29, v29, v29 row_half_mirror row_mask:0xf bank_mask:0xf
	v_max_u32_dpp v26, v26, v26 row_mirror row_mask:0xf bank_mask:0xf
	v_max_u32_dpp v27, v27, v27 row_mirror row_mask:0xf bank_mask:0xf
	v_max_u32_dpp v28, v28, v28 row_mirror row_mask:0xf bank_mask:0xf
	v_max_u32_dpp v29, v29, v29 row_mirror row_mask:0xf bank_mask:0xf
	v_max_u32_dpp v26, v26, v26 row_bcast:15 row_mask:0xa bank_mask:0xf
	v_max_u32_dpp v27, v27, v27 row_bcast:15 row_mask:0xa bank_mask:0xf
	v_max_u32_dpp v28, v28, v28 row_bcast:15 row_mask:0xa bank_mask:0xf
	v_max_u32_dpp v29, v29, v29 row_bcast:15 row_mask:0xa bank_mask:0xf
	v_max_u32_dpp v26, v26, v26 row_bcast:31 row_mask:0xc bank_mask:0xf
	v_max_u32_dpp v27, v27, v27 row_bcast:31 row_mask:0xc bank_mask:0xf
	v_max_u32_dpp v28, v28, v28 row_bcast:31 row_mask:0xc bank_mask:0xf
	v_max_u32_dpp v29, v29, v29 row_bcast:31 row_mask:0xc bank_mask:0xf
	v_readlane_b32 s14, v26, 63
	v_readlane_b32 s15, v27, 63
	v_readlane_b32 s34, v28, 63
	v_readlane_b32 s35, v29, 63
	v_writelane_b32 v82, s14, 7
	v_writelane_b32 v83, s15, 7
	v_writelane_b32 v84, s34, 7
	v_writelane_b32 v85, s35, 7
	v_cmp_ne_u32_e64 s[42:43], s14, v18
	v_cmp_ne_u32_e64 s[66:67], s14, v22
	v_cmp_ne_u32_e64 s[0:1], s15, v19
	v_cmp_ne_u32_e32 vcc, s15, v23
	v_cndmask_b32_e64 v18, 0, v18, s[42:43]
	v_cndmask_b32_e64 v22, 0, v22, s[66:67]
	v_cndmask_b32_e64 v19, 0, v19, s[0:1]
	v_cndmask_b32_e32 v23, 0, v23, vcc
	v_cmp_ne_u32_e64 s[42:43], s34, v20
	v_cmp_ne_u32_e64 s[66:67], s34, v24
	v_cmp_ne_u32_e64 s[0:1], s35, v21
	v_cmp_ne_u32_e32 vcc, s35, v25
	v_cndmask_b32_e64 v20, 0, v20, s[42:43]
	v_cndmask_b32_e64 v24, 0, v24, s[66:67]
	v_cndmask_b32_e64 v21, 0, v21, s[0:1]
	v_cndmask_b32_e32 v25, 0, v25, vcc
	v_max_u32_e32 v26, v18, v22
	v_max_u32_e32 v27, v19, v23
	v_max_u32_e32 v28, v20, v24
	v_max_u32_e32 v29, v21, v25
	v_max_u32_dpp v26, v26, v26 quad_perm:[1,0,3,2] row_mask:0xf bank_mask:0xf
	v_max_u32_dpp v27, v27, v27 quad_perm:[1,0,3,2] row_mask:0xf bank_mask:0xf
	v_max_u32_dpp v28, v28, v28 quad_perm:[1,0,3,2] row_mask:0xf bank_mask:0xf
	v_max_u32_dpp v29, v29, v29 quad_perm:[1,0,3,2] row_mask:0xf bank_mask:0xf
	v_max_u32_dpp v26, v26, v26 quad_perm:[2,3,0,1] row_mask:0xf bank_mask:0xf
	v_max_u32_dpp v27, v27, v27 quad_perm:[2,3,0,1] row_mask:0xf bank_mask:0xf
	v_max_u32_dpp v28, v28, v28 quad_perm:[2,3,0,1] row_mask:0xf bank_mask:0xf
	v_max_u32_dpp v29, v29, v29 quad_perm:[2,3,0,1] row_mask:0xf bank_mask:0xf
	v_max_u32_dpp v26, v26, v26 row_half_mirror row_mask:0xf bank_mask:0xf
	v_max_u32_dpp v27, v27, v27 row_half_mirror row_mask:0xf bank_mask:0xf
	v_max_u32_dpp v28, v28, v28 row_half_mirror row_mask:0xf bank_mask:0xf
	v_max_u32_dpp v29, v29, v29 row_half_mirror row_mask:0xf bank_mask:0xf
	v_max_u32_dpp v26, v26, v26 row_mirror row_mask:0xf bank_mask:0xf
	v_max_u32_dpp v27, v27, v27 row_mirror row_mask:0xf bank_mask:0xf
	v_max_u32_dpp v28, v28, v28 row_mirror row_mask:0xf bank_mask:0xf
	v_max_u32_dpp v29, v29, v29 row_mirror row_mask:0xf bank_mask:0xf
	v_max_u32_dpp v26, v26, v26 row_bcast:15 row_mask:0xa bank_mask:0xf
	v_max_u32_dpp v27, v27, v27 row_bcast:15 row_mask:0xa bank_mask:0xf
	v_max_u32_dpp v28, v28, v28 row_bcast:15 row_mask:0xa bank_mask:0xf
	v_max_u32_dpp v29, v29, v29 row_bcast:15 row_mask:0xa bank_mask:0xf
	v_max_u32_dpp v26, v26, v26 row_bcast:31 row_mask:0xc bank_mask:0xf
	v_max_u32_dpp v27, v27, v27 row_bcast:31 row_mask:0xc bank_mask:0xf
	v_max_u32_dpp v28, v28, v28 row_bcast:31 row_mask:0xc bank_mask:0xf
	v_max_u32_dpp v29, v29, v29 row_bcast:31 row_mask:0xc bank_mask:0xf
	v_readlane_b32 s14, v26, 63
	v_readlane_b32 s15, v27, 63
	v_readlane_b32 s34, v28, 63
	v_readlane_b32 s35, v29, 63
	v_writelane_b32 v82, s14, 8
	v_writelane_b32 v83, s15, 8
	v_writelane_b32 v84, s34, 8
	v_writelane_b32 v85, s35, 8
	v_cmp_ne_u32_e64 s[42:43], s14, v18
	v_cmp_ne_u32_e64 s[66:67], s14, v22
	v_cmp_ne_u32_e64 s[0:1], s15, v19
	v_cmp_ne_u32_e32 vcc, s15, v23
	v_cndmask_b32_e64 v18, 0, v18, s[42:43]
	v_cndmask_b32_e64 v22, 0, v22, s[66:67]
	v_cndmask_b32_e64 v19, 0, v19, s[0:1]
	v_cndmask_b32_e32 v23, 0, v23, vcc
	v_cmp_ne_u32_e64 s[42:43], s34, v20
	v_cmp_ne_u32_e64 s[66:67], s34, v24
; __device__ __forceinline__ void nsa_quad_pre(int bg, int quad, const bf16_t* Q, const bf16_t* KV, const bf16_t* KCMP, const bf16_t* VCMPT, const float* GN, bf16_t* ONSA, ...
;     ...
;             for (int it = 0; it < 13; ++it) {
;                 unsigned m = k0 > k1 ? k0 : k1;
; #pragma unroll
;                 for (int off = 32; off >= 1; off >>= 1) { const unsigned o = (unsigned)__shfl_xor((int)m, off); m = o > m ? o : m; }
;                 if (k0 == m) k0 = 0u; if (k1 == m) k1 = 0u;
;                 if (lane == 0) selq[tt * 16 + it] = 127 - (int)(m & 127u);
	v_cmp_ne_u32_e64 s[0:1], s35, v21
	v_cmp_ne_u32_e32 vcc, s35, v25
	v_cndmask_b32_e64 v20, 0, v20, s[42:43]
	v_cndmask_b32_e64 v24, 0, v24, s[66:67]
	v_cndmask_b32_e64 v21, 0, v21, s[0:1]
	v_cndmask_b32_e32 v25, 0, v25, vcc
	v_max_u32_e32 v26, v18, v22
	v_max_u32_e32 v27, v19, v23
	v_max_u32_e32 v28, v20, v24
	v_max_u32_e32 v29, v21, v25
	v_max_u32_dpp v26, v26, v26 quad_perm:[1,0,3,2] row_mask:0xf bank_mask:0xf
	v_max_u32_dpp v27, v27, v27 quad_perm:[1,0,3,2] row_mask:0xf bank_mask:0xf
	v_max_u32_dpp v28, v28, v28 quad_perm:[1,0,3,2] row_mask:0xf bank_mask:0xf
	v_max_u32_dpp v29, v29, v29 quad_perm:[1,0,3,2] row_mask:0xf bank_mask:0xf
	v_max_u32_dpp v26, v26, v26 quad_perm:[2,3,0,1] row_mask:0xf bank_mask:0xf
	v_max_u32_dpp v27, v27, v27 quad_perm:[2,3,0,1] row_mask:0xf bank_mask:0xf
	v_max_u32_dpp v28, v28, v28 quad_perm:[2,3,0,1] row_mask:0xf bank_mask:0xf
	v_max_u32_dpp v29, v29, v29 quad_perm:[2,3,0,1] row_mask:0xf bank_mask:0xf
	v_max_u32_dpp v26, v26, v26 row_half_mirror row_mask:0xf bank_mask:0xf
	v_max_u32_dpp v27, v27, v27 row_half_mirror row_mask:0xf bank_mask:0xf
	v_max_u32_dpp v28, v28, v28 row_half_mirror row_mask:0xf bank_mask:0xf
	v_max_u32_dpp v29, v29, v29 row_half_mirror row_mask:0xf bank_mask:0xf
	v_max_u32_dpp v26, v26, v26 row_mirror row_mask:0xf bank_mask:0xf
	v_max_u32_dpp v27, v27, v27 row_mirror row_mask:0xf bank_mask:0xf
	v_max_u32_dpp v28, v28, v28 row_mirror row_mask:0xf bank_mask:0xf
	v_max_u32_dpp v29, v29, v29 row_mirror row_mask:0xf bank_mask:0xf
	v_max_u32_dpp v26, v26, v26 row_bcast:15 row_mask:0xa bank_mask:0xf
	v_max_u32_dpp v27, v27, v27 row_bcast:15 row_mask:0xa bank_mask:0xf
	v_max_u32_dpp v28, v28, v28 row_bcast:15 row_mask:0xa bank_mask:0xf
	v_max_u32_dpp v29, v29, v29 row_bcast:15 row_mask:0xa bank_mask:0xf
	v_max_u32_dpp v26, v26, v26 row_bcast:31 row_mask:0xc bank_mask:0xf
	v_max_u32_dpp v27, v27, v27 row_bcast:31 row_mask:0xc bank_mask:0xf
	v_max_u32_dpp v28, v28, v28 row_bcast:31 row_mask:0xc bank_mask:0xf
	v_max_u32_dpp v29, v29, v29 row_bcast:31 row_mask:0xc bank_mask:0xf
	v_readlane_b32 s14, v26, 63
	v_readlane_b32 s15, v27, 63
	v_readlane_b32 s34, v28, 63
	v_readlane_b32 s35, v29, 63
	v_writelane_b32 v82, s14, 9
	v_writelane_b32 v83, s15, 9
	v_writelane_b32 v84, s34, 9
	v_writelane_b32 v85, s35, 9
	v_cmp_ne_u32_e64 s[42:43], s14, v18
	v_cmp_ne_u32_e64 s[66:67], s14, v22
	v_cmp_ne_u32_e64 s[0:1], s15, v19
	v_cmp_ne_u32_e32 vcc, s15, v23
	v_cndmask_b32_e64 v18, 0, v18, s[42:43]
	v_cndmask_b32_e64 v22, 0, v22, s[66:67]
	v_cndmask_b32_e64 v19, 0, v19, s[0:1]
	v_cndmask_b32_e32 v23, 0, v23, vcc
	v_cmp_ne_u32_e64 s[42:43], s34, v20
	v_cmp_ne_u32_e64 s[66:67], s34, v24
	v_cmp_ne_u32_e64 s[0:1], s35, v21
	v_cmp_ne_u32_e32 vcc, s35, v25
	v_cndmask_b32_e64 v20, 0, v20, s[42:43]
	v_cndmask_b32_e64 v24, 0, v24, s[66:67]
	v_cndmask_b32_e64 v21, 0, v21, s[0:1]
	v_cndmask_b32_e32 v25, 0, v25, vcc
	v_max_u32_e32 v26, v18, v22
	v_max_u32_e32 v27, v19, v23
	v_max_u32_e32 v28, v20, v24
	v_max_u32_e32 v29, v21, v25
	v_max_u32_dpp v26, v26, v26 quad_perm:[1,0,3,2] row_mask:0xf bank_mask:0xf
	v_max_u32_dpp v27, v27, v27 quad_perm:[1,0,3,2] row_mask:0xf bank_mask:0xf
	v_max_u32_dpp v28, v28, v28 quad_perm:[1,0,3,2] row_mask:0xf bank_mask:0xf
	v_max_u32_dpp v29, v29, v29 quad_perm:[1,0,3,2] row_mask:0xf bank_mask:0xf
	v_max_u32_dpp v26, v26, v26 quad_perm:[2,3,0,1] row_mask:0xf bank_mask:0xf
	v_max_u32_dpp v27, v27, v27 quad_perm:[2,3,0,1] row_mask:0xf bank_mask:0xf
	v_max_u32_dpp v28, v28, v28 quad_perm:[2,3,0,1] row_mask:0xf bank_mask:0xf
	v_max_u32_dpp v29, v29, v29 quad_perm:[2,3,0,1] row_mask:0xf bank_mask:0xf
	v_max_u32_dpp v26, v26, v26 row_half_mirror row_mask:0xf bank_mask:0xf
	v_max_u32_dpp v27, v27, v27 row_half_mirror row_mask:0xf bank_mask:0xf
	v_max_u32_dpp v28, v28, v28 row_half_mirror row_mask:0xf bank_mask:0xf
	v_max_u32_dpp v29, v29, v29 row_half_mirror row_mask:0xf bank_mask:0xf
	v_max_u32_dpp v26, v26, v26 row_mirror row_mask:0xf bank_mask:0xf
	v_max_u32_dpp v27, v27, v27 row_mirror row_mask:0xf bank_mask:0xf
	v_max_u32_dpp v28, v28, v28 row_mirror row_mask:0xf bank_mask:0xf
	v_max_u32_dpp v29, v29, v29 row_mirror row_mask:0xf bank_mask:0xf
	v_max_u32_dpp v26, v26, v26 row_bcast:15 row_mask:0xa bank_mask:0xf
	v_max_u32_dpp v27, v27, v27 row_bcast:15 row_mask:0xa bank_mask:0xf
	v_max_u32_dpp v28, v28, v28 row_bcast:15 row_mask:0xa bank_mask:0xf
	v_max_u32_dpp v29, v29, v29 row_bcast:15 row_mask:0xa bank_mask:0xf
	v_max_u32_dpp v26, v26, v26 row_bcast:31 row_mask:0xc bank_mask:0xf
	v_max_u32_dpp v27, v27, v27 row_bcast:31 row_mask:0xc bank_mask:0xf
	v_max_u32_dpp v28, v28, v28 row_bcast:31 row_mask:0xc bank_mask:0xf
	v_max_u32_dpp v29, v29, v29 row_bcast:31 row_mask:0xc bank_mask:0xf
	v_readlane_b32 s14, v26, 63
	v_readlane_b32 s15, v27, 63
	v_readlane_b32 s34, v28, 63
	v_readlane_b32 s35, v29, 63
	v_writelane_b32 v82, s14, 10
	v_writelane_b32 v83, s15, 10
	v_writelane_b32 v84, s34, 10
	v_writelane_b32 v85, s35, 10
	v_cmp_ne_u32_e64 s[42:43], s14, v18
	v_cmp_ne_u32_e64 s[66:67], s14, v22
	v_cmp_ne_u32_e64 s[0:1], s15, v19
	v_cmp_ne_u32_e32 vcc, s15, v23
	v_cndmask_b32_e64 v18, 0, v18, s[42:43]
	v_cndmask_b32_e64 v22, 0, v22, s[66:67]
	v_cndmask_b32_e64 v19, 0, v19, s[0:1]
	v_cndmask_b32_e32 v23, 0, v23, vcc
	v_cmp_ne_u32_e64 s[42:43], s34, v20
	v_cmp_ne_u32_e64 s[66:67], s34, v24
	v_cmp_ne_u32_e64 s[0:1], s35, v21
	v_cmp_ne_u32_e32 vcc, s35, v25
	v_cndmask_b32_e64 v20, 0, v20, s[42:43]
	v_cndmask_b32_e64 v24, 0, v24, s[66:67]
	v_cndmask_b32_e64 v21, 0, v21, s[0:1]
	v_cndmask_b32_e32 v25, 0, v25, vcc
	v_max_u32_e32 v26, v18, v22
	v_max_u32_e32 v27, v19, v23
	v_max_u32_e32 v28, v20, v24
; __device__ __forceinline__ void nsa_quad_pre(int bg, int quad, const bf16_t* Q, const bf16_t* KV, const bf16_t* KCMP, const bf16_t* VCMPT, const float* GN, bf16_t* ONSA, ...
;     ...
;             for (int it = 0; it < 13; ++it) {
;                 unsigned m = k0 > k1 ? k0 : k1;
; #pragma unroll
;                 for (int off = 32; off >= 1; off >>= 1) { const unsigned o = (unsigned)__shfl_xor((int)m, off); m = o > m ? o : m; }
;                 if (k0 == m) k0 = 0u; if (k1 == m) k1 = 0u;
;                 if (lane == 0) selq[tt * 16 + it] = 127 - (int)(m & 127u);
;             }
;             if (lane == 0) { selq[tt * 16 + 13] = 0; selq[tt * 16 + 14] = cur - 1; selq[tt * 16 + 15] = cur; }
	v_max_u32_e32 v29, v21, v25
	v_max_u32_dpp v26, v26, v26 quad_perm:[1,0,3,2] row_mask:0xf bank_mask:0xf
	v_max_u32_dpp v27, v27, v27 quad_perm:[1,0,3,2] row_mask:0xf bank_mask:0xf
	v_max_u32_dpp v28, v28, v28 quad_perm:[1,0,3,2] row_mask:0xf bank_mask:0xf
	v_max_u32_dpp v29, v29, v29 quad_perm:[1,0,3,2] row_mask:0xf bank_mask:0xf
	v_max_u32_dpp v26, v26, v26 quad_perm:[2,3,0,1] row_mask:0xf bank_mask:0xf
	v_max_u32_dpp v27, v27, v27 quad_perm:[2,3,0,1] row_mask:0xf bank_mask:0xf
	v_max_u32_dpp v28, v28, v28 quad_perm:[2,3,0,1] row_mask:0xf bank_mask:0xf
	v_max_u32_dpp v29, v29, v29 quad_perm:[2,3,0,1] row_mask:0xf bank_mask:0xf
	v_max_u32_dpp v26, v26, v26 row_half_mirror row_mask:0xf bank_mask:0xf
	v_max_u32_dpp v27, v27, v27 row_half_mirror row_mask:0xf bank_mask:0xf
	v_max_u32_dpp v28, v28, v28 row_half_mirror row_mask:0xf bank_mask:0xf
	v_max_u32_dpp v29, v29, v29 row_half_mirror row_mask:0xf bank_mask:0xf
	v_max_u32_dpp v26, v26, v26 row_mirror row_mask:0xf bank_mask:0xf
	v_max_u32_dpp v27, v27, v27 row_mirror row_mask:0xf bank_mask:0xf
	v_max_u32_dpp v28, v28, v28 row_mirror row_mask:0xf bank_mask:0xf
	v_max_u32_dpp v29, v29, v29 row_mirror row_mask:0xf bank_mask:0xf
	v_max_u32_dpp v26, v26, v26 row_bcast:15 row_mask:0xa bank_mask:0xf
	v_max_u32_dpp v27, v27, v27 row_bcast:15 row_mask:0xa bank_mask:0xf
	v_max_u32_dpp v28, v28, v28 row_bcast:15 row_mask:0xa bank_mask:0xf
	v_max_u32_dpp v29, v29, v29 row_bcast:15 row_mask:0xa bank_mask:0xf
	v_max_u32_dpp v26, v26, v26 row_bcast:31 row_mask:0xc bank_mask:0xf
	v_max_u32_dpp v27, v27, v27 row_bcast:31 row_mask:0xc bank_mask:0xf
	v_max_u32_dpp v28, v28, v28 row_bcast:31 row_mask:0xc bank_mask:0xf
	v_max_u32_dpp v29, v29, v29 row_bcast:31 row_mask:0xc bank_mask:0xf
	v_readlane_b32 s14, v26, 63
	v_readlane_b32 s15, v27, 63
	v_readlane_b32 s34, v28, 63
	v_readlane_b32 s35, v29, 63
	v_writelane_b32 v82, s14, 11
	v_writelane_b32 v83, s15, 11
	v_writelane_b32 v84, s34, 11
	v_writelane_b32 v85, s35, 11
	v_cmp_ne_u32_e64 s[42:43], s14, v18
	v_cmp_ne_u32_e64 s[66:67], s14, v22
	v_cmp_ne_u32_e64 s[0:1], s15, v19
	v_cmp_ne_u32_e32 vcc, s15, v23
	v_cndmask_b32_e64 v18, 0, v18, s[42:43]
	v_cndmask_b32_e64 v22, 0, v22, s[66:67]
	v_cndmask_b32_e64 v19, 0, v19, s[0:1]
	v_cndmask_b32_e32 v23, 0, v23, vcc
	v_cmp_ne_u32_e64 s[42:43], s34, v20
	v_cmp_ne_u32_e64 s[66:67], s34, v24
	v_cmp_ne_u32_e64 s[0:1], s35, v21
	v_cmp_ne_u32_e32 vcc, s35, v25
	v_cndmask_b32_e64 v20, 0, v20, s[42:43]
	v_cndmask_b32_e64 v24, 0, v24, s[66:67]
	v_cndmask_b32_e64 v21, 0, v21, s[0:1]
	v_cndmask_b32_e32 v25, 0, v25, vcc
	v_max_u32_e32 v26, v18, v22
	v_max_u32_e32 v27, v19, v23
	v_max_u32_e32 v28, v20, v24
	v_max_u32_e32 v29, v21, v25
	v_max_u32_dpp v26, v26, v26 quad_perm:[1,0,3,2] row_mask:0xf bank_mask:0xf
	v_max_u32_dpp v27, v27, v27 quad_perm:[1,0,3,2] row_mask:0xf bank_mask:0xf
	v_max_u32_dpp v28, v28, v28 quad_perm:[1,0,3,2] row_mask:0xf bank_mask:0xf
	v_max_u32_dpp v29, v29, v29 quad_perm:[1,0,3,2] row_mask:0xf bank_mask:0xf
	v_max_u32_dpp v26, v26, v26 quad_perm:[2,3,0,1] row_mask:0xf bank_mask:0xf
	v_max_u32_dpp v27, v27, v27 quad_perm:[2,3,0,1] row_mask:0xf bank_mask:0xf
	v_max_u32_dpp v28, v28, v28 quad_perm:[2,3,0,1] row_mask:0xf bank_mask:0xf
	v_max_u32_dpp v29, v29, v29 quad_perm:[2,3,0,1] row_mask:0xf bank_mask:0xf
	v_max_u32_dpp v26, v26, v26 row_half_mirror row_mask:0xf bank_mask:0xf
	v_max_u32_dpp v27, v27, v27 row_half_mirror row_mask:0xf bank_mask:0xf
	v_max_u32_dpp v28, v28, v28 row_half_mirror row_mask:0xf bank_mask:0xf
	v_max_u32_dpp v29, v29, v29 row_half_mirror row_mask:0xf bank_mask:0xf
	v_max_u32_dpp v26, v26, v26 row_mirror row_mask:0xf bank_mask:0xf
	v_max_u32_dpp v27, v27, v27 row_mirror row_mask:0xf bank_mask:0xf
	v_max_u32_dpp v28, v28, v28 row_mirror row_mask:0xf bank_mask:0xf
	v_max_u32_dpp v29, v29, v29 row_mirror row_mask:0xf bank_mask:0xf
	v_max_u32_dpp v26, v26, v26 row_bcast:15 row_mask:0xa bank_mask:0xf
	v_max_u32_dpp v27, v27, v27 row_bcast:15 row_mask:0xa bank_mask:0xf
	v_max_u32_dpp v28, v28, v28 row_bcast:15 row_mask:0xa bank_mask:0xf
	v_max_u32_dpp v29, v29, v29 row_bcast:15 row_mask:0xa bank_mask:0xf
	v_max_u32_dpp v26, v26, v26 row_bcast:31 row_mask:0xc bank_mask:0xf
	v_max_u32_dpp v27, v27, v27 row_bcast:31 row_mask:0xc bank_mask:0xf
	v_max_u32_dpp v28, v28, v28 row_bcast:31 row_mask:0xc bank_mask:0xf
	v_max_u32_dpp v29, v29, v29 row_bcast:31 row_mask:0xc bank_mask:0xf
	v_readlane_b32 s14, v26, 63
	v_readlane_b32 s15, v27, 63
	v_readlane_b32 s34, v28, 63
	v_readlane_b32 s35, v29, 63
	v_writelane_b32 v82, s14, 12
	v_writelane_b32 v83, s15, 12
	v_writelane_b32 v84, s34, 12
	v_writelane_b32 v85, s35, 12
	v_and_b32_e32 v82, 127, v82
	v_sub_u32_e32 v82, 127, v82
	v_and_b32_e32 v83, 127, v83
	v_sub_u32_e32 v83, 127, v83
	v_and_b32_e32 v84, 127, v84
	v_sub_u32_e32 v84, 127, v84
	v_and_b32_e32 v85, 127, v85
	v_sub_u32_e32 v85, 127, v85
	s_add_i32 s19, s18, -1
	v_mov_b32_e32 v236, s19
	v_mov_b32_e32 v237, s18
	v_cmp_eq_u32_e64 s[14:15], 14, v184
	v_cmp_eq_u32_e64 s[34:35], 15, v184
	s_nop 0
	v_cndmask_b32_e64 v82, v82, v236, s[14:15]
	v_cndmask_b32_e64 v82, v82, v237, s[34:35]
	v_cndmask_b32_e64 v83, v83, v236, s[14:15]
	v_cndmask_b32_e64 v83, v83, v237, s[34:35]
	v_cndmask_b32_e64 v84, v84, v236, s[14:15]
	v_cndmask_b32_e64 v84, v84, v237, s[34:35]
	v_cndmask_b32_e64 v85, v85, v236, s[14:15]
	v_cndmask_b32_e64 v85, v85, v237, s[34:35]
	s_and_saveexec_b64 s[42:43], s[6:7]
	ds_write_b32 v196, v82 offset:51264
	ds_write_b32 v196, v83 offset:51328
	ds_write_b32 v196, v84 offset:51392
	ds_write_b32 v196, v85 offset:51456
	s_or_b64 exec, exec, s[42:43]
	s_branch .Ltopk_done_q0

; #define LAS __attribute__((address_space(3)))
; #define CBAR() asm volatile("" ::: "memory")
; __device__ __forceinline__ void nsa_quad_pre(int bg, int quad, const bf16_t* Q, const bf16_t* KV, const bf16_t* KCMP, const bf16_t* VCMPT, const float* GN, bf16_t* ONSA, ...
;     ...
;         for (int gr = 0; gr < ngr; ++gr) {
;             const bool more = gr + 1 < ngr;
;             qk_scores(KF, qf, sc);
;             if (more) load_k(KF, KP_C(gr + 1));
;             cmp_sm2(sc, gr, t0, bt, inv, Pb, psum, r16, q4);
;             pv_step(VF, oc, Pb, r16, q4);
;             if (more) load_v(VF, VP_C(gr + 1));
;         }
;     }
;     CBAR();
; #pragma unroll
;     for (int tt = 0; tt < 4; ++tt) {
;         const int tok = t0 + tt, cur = tok >> 6;
;         if (cur < 16) { if (lane < 16) selq[tt * 16 + lane] = lane; }
;         else {
;             unsigned k0 = 0u, k1 = 0u;
;             { const int j = lane; if (j >= 1 && j <= cur - 2) { const LAS float* ps = psum + tt * 512 + 4 * j - 1; const float v = ps[0] + ps[1] + ps[2] + ps[3] + ps[4]; k0 = (__builtin_bit_cast(unsigned, v) & ~127u) | (unsigned)(127 - j); } }
;             { const int j = lane + 64; if (j <= cur - 2) { const LAS float* ps = psum + tt * 512 + 4 * j - 1; const float v = ps[0] + ps[1] + ps[2] + ps[3] + ps[4]; k1 = (__builtin_bit_cast(unsigned, v) & ~127u) | (unsigned)(127 - j); } }
;             for (int it = 0; it < 13; ++it) {
;                 unsigned m = k0 > k1 ? k0 : k1;
; #pragma unroll
;                 for (int off = 32; off >= 1; off >>= 1) { const unsigned o = (unsigned)__shfl_xor((int)m, off); m = o > m ? o : m; }
;                 if (k0 == m) k0 = 0u; if (k1 == m) k1 = 0u;
;                 if (lane == 0) selq[tt * 16 + it] = 127 - (int)(m & 127u);
;             }
;             if (lane == 0) { selq[tt * 16 + 13] = 0; selq[tt * 16 + 14] = cur - 1; selq[tt * 16 + 15] = cur; }
.Lcmp_tail_q1p2:
	s_add_i32 s75, s75, 1
	s_cmp_eq_u32 s75, 3
	s_cselect_b32 s75, 0, s75
	s_add_i32 s57, s57, 1
	s_cmp_lt_i32 s57, s74
	s_waitcnt vmcnt(2) lgkmcnt(0)
	s_barrier
	s_cbranch_scc1 .Lcmp_top_q1p2
	s_waitcnt lgkmcnt(0)
	s_nop 7
	s_nop 3
	v_and_b32_e32 v232, 15, v184
	v_lshrrev_b32_e32 v233, 4, v184
	v_and_b32_e32 v234, 3, v232
	v_lshrrev_b32_e32 v235, 2, v232
	s_add_i32 s0, s47, s97
	v_add_u32_e32 v253, s0, v234
	s_and_b32 s1, s88, 3
	s_lshl_b32 s1, s1, 2
	v_add_u32_e32 v0, s1, v235
	v_lshlrev_b32_e32 v98, 7, v0
	v_lshl_add_u32 v98, v253, 11, v98
	v_lshl_add_u32 v98, v233, 3, v98
	s_add_u32 s14, s30, 0xf900000
	s_addc_u32 s15, s31, 0
	s_waitcnt vmcnt(0)
	v_mul_f32_e32 v2, v2, v227
	v_mul_f32_e32 v3, v3, v227
	v_mul_f32_e32 v4, v4, v227
	v_mul_f32_e32 v5, v5, v227
	v_mul_f32_e32 v6, v6, v227
	v_mul_f32_e32 v7, v7, v227
	v_mul_f32_e32 v8, v8, v227
	v_mul_f32_e32 v9, v9, v227
	v_mul_f32_e32 v10, v10, v227
	v_mul_f32_e32 v11, v11, v227
	v_mul_f32_e32 v12, v12, v227
	v_mul_f32_e32 v13, v13, v227
	v_mul_f32_e32 v14, v14, v227
	v_mul_f32_e32 v15, v15, v227
	v_mul_f32_e32 v16, v16, v227
	v_mul_f32_e32 v17, v17, v227
	v_cvt_pk_bf16_f32 v216, v2, v3
	v_cvt_pk_bf16_f32 v217, v4, v5
	v_cvt_pk_bf16_f32 v218, v6, v7
	v_cvt_pk_bf16_f32 v219, v8, v9
	v_cvt_pk_bf16_f32 v220, v10, v11
	v_cvt_pk_bf16_f32 v221, v12, v13
	v_cvt_pk_bf16_f32 v222, v14, v15
	v_cvt_pk_bf16_f32 v223, v16, v17
	global_store_dwordx2 v98, v[216:217], s[14:15] offset:0
	global_store_dwordx2 v98, v[218:219], s[14:15] offset:32
	global_store_dwordx2 v98, v[220:221], s[14:15] offset:64
	global_store_dwordx2 v98, v[222:223], s[14:15] offset:96
	s_waitcnt lgkmcnt(0)
	s_cmp_gt_i32 s18, 15
	s_cbranch_scc0 .Ltopk_small_q1
	s_lshl_b32 s19, s80, 10
	s_add_i32 s19, s19, 56384
	v_lshlrev_b32_e32 v96, 4, v184
	v_add_u32_e32 v96, s19, v96
	v_add_u32_e32 v97, 0xfffffffc, v96
	v_sub_u32_e32 v94, 127, v184
	v_sub_u32_e32 v95, 63, v184
	s_mov_b32 s54, 0xffffff80
	s_add_i32 s21, s18, -2
	v_add_u32_e32 v236, 64, v184
	ds_read_b32 v86, v97 offset:0
	ds_read_b128 v[50:53], v96 offset:0
	ds_read_b32 v87, v97 offset:1024
	ds_read_b128 v[54:57], v96 offset:1024
	ds_read_b32 v88, v97 offset:2048
	ds_read_b128 v[58:61], v96 offset:2048
	ds_read_b32 v89, v97 offset:3072
	ds_read_b128 v[62:65], v96 offset:3072
	s_waitcnt lgkmcnt(6)
	v_add_f32_e32 v86, v86, v50
	v_add_f32_e32 v86, v86, v51
	v_add_f32_e32 v86, v86, v52
	v_add_f32_e32 v86, v86, v53
	v_and_or_b32 v18, v86, s54, v94
	s_waitcnt lgkmcnt(4)
	v_add_f32_e32 v87, v87, v54
	v_add_f32_e32 v87, v87, v55
	v_add_f32_e32 v87, v87, v56
	v_add_f32_e32 v87, v87, v57
	v_and_or_b32 v22, v87, s54, v95
	s_waitcnt lgkmcnt(2)
	v_add_f32_e32 v88, v88, v58
	v_add_f32_e32 v88, v88, v59
	v_add_f32_e32 v88, v88, v60
	v_add_f32_e32 v88, v88, v61
	v_and_or_b32 v19, v88, s54, v94
	s_waitcnt lgkmcnt(0)
	v_add_f32_e32 v89, v89, v62
	v_add_f32_e32 v89, v89, v63
	v_add_f32_e32 v89, v89, v64
	v_add_f32_e32 v89, v89, v65
	v_and_or_b32 v23, v89, s54, v95
	ds_read_b32 v90, v97 offset:4096
	ds_read_b128 v[66:69], v96 offset:4096
	ds_read_b32 v91, v97 offset:5120
	ds_read_b128 v[70:73], v96 offset:5120
	ds_read_b32 v92, v97 offset:6144
	ds_read_b128 v[74:77], v96 offset:6144
	ds_read_b32 v93, v97 offset:7168
	ds_read_b128 v[78:81], v96 offset:7168
	s_waitcnt lgkmcnt(6)
	v_add_f32_e32 v90, v90, v66
	v_add_f32_e32 v90, v90, v67
	v_add_f32_e32 v90, v90, v68
	v_add_f32_e32 v90, v90, v69
	v_and_or_b32 v20, v90, s54, v94
	s_waitcnt lgkmcnt(4)
	v_add_f32_e32 v91, v91, v70
	v_add_f32_e32 v91, v91, v71
	v_add_f32_e32 v91, v91, v72
	v_add_f32_e32 v91, v91, v73
	v_and_or_b32 v24, v91, s54, v95
	s_waitcnt lgkmcnt(2)
	v_add_f32_e32 v92, v92, v74
	v_add_f32_e32 v92, v92, v75
	v_add_f32_e32 v92, v92, v76
	v_add_f32_e32 v92, v92, v77
	v_and_or_b32 v21, v92, s54, v94
	s_waitcnt lgkmcnt(0)
	v_add_f32_e32 v93, v93, v78
	v_add_f32_e32 v93, v93, v79
	v_add_f32_e32 v93, v93, v80
	v_add_f32_e32 v93, v93, v81
	v_and_or_b32 v25, v93, s54, v95
	v_cmp_le_i32_e64 s[14:15], v184, s21
	v_cmp_lt_i32_e64 s[34:35], 0, v184
	s_nop 0
	s_and_b64 s[14:15], s[14:15], s[34:35]
	v_cmp_le_i32_e64 s[34:35], v236, s21
	v_cndmask_b32_e64 v18, 0, v18, s[14:15]
	s_nop 0
	v_cndmask_b32_e64 v22, 0, v22, s[34:35]
	v_mov_b32_e32 v82, 127
	v_cndmask_b32_e64 v19, 0, v19, s[14:15]
	v_cndmask_b32_e64 v23, 0, v23, s[34:35]
	v_mov_b32_e32 v83, 127
	v_cndmask_b32_e64 v20, 0, v20, s[14:15]
	v_cndmask_b32_e64 v24, 0, v24, s[34:35]
	v_mov_b32_e32 v84, 127
	v_cndmask_b32_e64 v21, 0, v21, s[14:15]
	v_cndmask_b32_e64 v25, 0, v25, s[34:35]
	v_mov_b32_e32 v85, 127
	v_max_u32_e32 v26, v18, v22
	v_max_u32_e32 v27, v19, v23
	v_max_u32_e32 v28, v20, v24
	v_max_u32_e32 v29, v21, v25
	v_max_u32_dpp v26, v26, v26 quad_perm:[1,0,3,2] row_mask:0xf bank_mask:0xf
	v_max_u32_dpp v27, v27, v27 quad_perm:[1,0,3,2] row_mask:0xf bank_mask:0xf
	v_max_u32_dpp v28, v28, v28 quad_perm:[1,0,3,2] row_mask:0xf bank_mask:0xf
	v_max_u32_dpp v29, v29, v29 quad_perm:[1,0,3,2] row_mask:0xf bank_mask:0xf
	v_max_u32_dpp v26, v26, v26 quad_perm:[2,3,0,1] row_mask:0xf bank_mask:0xf
	v_max_u32_dpp v27, v27, v27 quad_perm:[2,3,0,1] row_mask:0xf bank_mask:0xf
	v_max_u32_dpp v28, v28, v28 quad_perm:[2,3,0,1] row_mask:0xf bank_mask:0xf
	v_max_u32_dpp v29, v29, v29 quad_perm:[2,3,0,1] row_mask:0xf bank_mask:0xf
	v_max_u32_dpp v26, v26, v26 row_half_mirror row_mask:0xf bank_mask:0xf
	v_max_u32_dpp v27, v27, v27 row_half_mirror row_mask:0xf bank_mask:0xf
	v_max_u32_dpp v28, v28, v28 row_half_mirror row_mask:0xf bank_mask:0xf
	v_max_u32_dpp v29, v29, v29 row_half_mirror row_mask:0xf bank_mask:0xf
	v_max_u32_dpp v26, v26, v26 row_mirror row_mask:0xf bank_mask:0xf
; __device__ __forceinline__ void nsa_quad_pre(int bg, int quad, const bf16_t* Q, const bf16_t* KV, const bf16_t* KCMP, const bf16_t* VCMPT, const float* GN, bf16_t* ONSA, ...
;     ...
;             for (int it = 0; it < 13; ++it) {
;                 unsigned m = k0 > k1 ? k0 : k1;
; #pragma unroll
;                 for (int off = 32; off >= 1; off >>= 1) { const unsigned o = (unsigned)__shfl_xor((int)m, off); m = o > m ? o : m; }
;                 if (k0 == m) k0 = 0u; if (k1 == m) k1 = 0u;
;                 if (lane == 0) selq[tt * 16 + it] = 127 - (int)(m & 127u);
	v_max_u32_dpp v27, v27, v27 row_mirror row_mask:0xf bank_mask:0xf
	v_max_u32_dpp v28, v28, v28 row_mirror row_mask:0xf bank_mask:0xf
	v_max_u32_dpp v29, v29, v29 row_mirror row_mask:0xf bank_mask:0xf
	v_max_u32_dpp v26, v26, v26 row_bcast:15 row_mask:0xa bank_mask:0xf
	v_max_u32_dpp v27, v27, v27 row_bcast:15 row_mask:0xa bank_mask:0xf
	v_max_u32_dpp v28, v28, v28 row_bcast:15 row_mask:0xa bank_mask:0xf
	v_max_u32_dpp v29, v29, v29 row_bcast:15 row_mask:0xa bank_mask:0xf
	v_max_u32_dpp v26, v26, v26 row_bcast:31 row_mask:0xc bank_mask:0xf
	v_max_u32_dpp v27, v27, v27 row_bcast:31 row_mask:0xc bank_mask:0xf
	v_max_u32_dpp v28, v28, v28 row_bcast:31 row_mask:0xc bank_mask:0xf
	v_max_u32_dpp v29, v29, v29 row_bcast:31 row_mask:0xc bank_mask:0xf
	v_readlane_b32 s14, v26, 63
	v_readlane_b32 s15, v27, 63
	v_readlane_b32 s34, v28, 63
	v_readlane_b32 s35, v29, 63
	v_writelane_b32 v82, s14, 0
	v_writelane_b32 v83, s15, 0
	v_writelane_b32 v84, s34, 0
	v_writelane_b32 v85, s35, 0
	v_cmp_ne_u32_e64 s[42:43], s14, v18
	v_cmp_ne_u32_e64 s[66:67], s14, v22
	v_cmp_ne_u32_e64 s[0:1], s15, v19
	v_cmp_ne_u32_e32 vcc, s15, v23
	v_cndmask_b32_e64 v18, 0, v18, s[42:43]
	v_cndmask_b32_e64 v22, 0, v22, s[66:67]
	v_cndmask_b32_e64 v19, 0, v19, s[0:1]
	v_cndmask_b32_e32 v23, 0, v23, vcc
	v_cmp_ne_u32_e64 s[42:43], s34, v20
	v_cmp_ne_u32_e64 s[66:67], s34, v24
	v_cmp_ne_u32_e64 s[0:1], s35, v21
	v_cmp_ne_u32_e32 vcc, s35, v25
	v_cndmask_b32_e64 v20, 0, v20, s[42:43]
	v_cndmask_b32_e64 v24, 0, v24, s[66:67]
	v_cndmask_b32_e64 v21, 0, v21, s[0:1]
	v_cndmask_b32_e32 v25, 0, v25, vcc
	v_max_u32_e32 v26, v18, v22
	v_max_u32_e32 v27, v19, v23
	v_max_u32_e32 v28, v20, v24
	v_max_u32_e32 v29, v21, v25
	v_max_u32_dpp v26, v26, v26 quad_perm:[1,0,3,2] row_mask:0xf bank_mask:0xf
	v_max_u32_dpp v27, v27, v27 quad_perm:[1,0,3,2] row_mask:0xf bank_mask:0xf
	v_max_u32_dpp v28, v28, v28 quad_perm:[1,0,3,2] row_mask:0xf bank_mask:0xf
	v_max_u32_dpp v29, v29, v29 quad_perm:[1,0,3,2] row_mask:0xf bank_mask:0xf
	v_max_u32_dpp v26, v26, v26 quad_perm:[2,3,0,1] row_mask:0xf bank_mask:0xf
	v_max_u32_dpp v27, v27, v27 quad_perm:[2,3,0,1] row_mask:0xf bank_mask:0xf
	v_max_u32_dpp v28, v28, v28 quad_perm:[2,3,0,1] row_mask:0xf bank_mask:0xf
	v_max_u32_dpp v29, v29, v29 quad_perm:[2,3,0,1] row_mask:0xf bank_mask:0xf
	v_max_u32_dpp v26, v26, v26 row_half_mirror row_mask:0xf bank_mask:0xf
	v_max_u32_dpp v27, v27, v27 row_half_mirror row_mask:0xf bank_mask:0xf
	v_max_u32_dpp v28, v28, v28 row_half_mirror row_mask:0xf bank_mask:0xf
	v_max_u32_dpp v29, v29, v29 row_half_mirror row_mask:0xf bank_mask:0xf
	v_max_u32_dpp v26, v26, v26 row_mirror row_mask:0xf bank_mask:0xf
	v_max_u32_dpp v27, v27, v27 row_mirror row_mask:0xf bank_mask:0xf
	v_max_u32_dpp v28, v28, v28 row_mirror row_mask:0xf bank_mask:0xf
	v_max_u32_dpp v29, v29, v29 row_mirror row_mask:0xf bank_mask:0xf
	v_max_u32_dpp v26, v26, v26 row_bcast:15 row_mask:0xa bank_mask:0xf
	v_max_u32_dpp v27, v27, v27 row_bcast:15 row_mask:0xa bank_mask:0xf
	v_max_u32_dpp v28, v28, v28 row_bcast:15 row_mask:0xa bank_mask:0xf
	v_max_u32_dpp v29, v29, v29 row_bcast:15 row_mask:0xa bank_mask:0xf
	v_max_u32_dpp v26, v26, v26 row_bcast:31 row_mask:0xc bank_mask:0xf
	v_max_u32_dpp v27, v27, v27 row_bcast:31 row_mask:0xc bank_mask:0xf
	v_max_u32_dpp v28, v28, v28 row_bcast:31 row_mask:0xc bank_mask:0xf
	v_max_u32_dpp v29, v29, v29 row_bcast:31 row_mask:0xc bank_mask:0xf
	v_readlane_b32 s14, v26, 63
	v_readlane_b32 s15, v27, 63
	v_readlane_b32 s34, v28, 63
	v_readlane_b32 s35, v29, 63
	v_writelane_b32 v82, s14, 1
	v_writelane_b32 v83, s15, 1
	v_writelane_b32 v84, s34, 1
	v_writelane_b32 v85, s35, 1
	v_cmp_ne_u32_e64 s[42:43], s14, v18
	v_cmp_ne_u32_e64 s[66:67], s14, v22
	v_cmp_ne_u32_e64 s[0:1], s15, v19
	v_cmp_ne_u32_e32 vcc, s15, v23
	v_cndmask_b32_e64 v18, 0, v18, s[42:43]
	v_cndmask_b32_e64 v22, 0, v22, s[66:67]
	v_cndmask_b32_e64 v19, 0, v19, s[0:1]
	v_cndmask_b32_e32 v23, 0, v23, vcc
	v_cmp_ne_u32_e64 s[42:43], s34, v20
	v_cmp_ne_u32_e64 s[66:67], s34, v24
	v_cmp_ne_u32_e64 s[0:1], s35, v21
	v_cmp_ne_u32_e32 vcc, s35, v25
	v_cndmask_b32_e64 v20, 0, v20, s[42:43]
	v_cndmask_b32_e64 v24, 0, v24, s[66:67]
	v_cndmask_b32_e64 v21, 0, v21, s[0:1]
	v_cndmask_b32_e32 v25, 0, v25, vcc
	v_max_u32_e32 v26, v18, v22
	v_max_u32_e32 v27, v19, v23
	v_max_u32_e32 v28, v20, v24
	v_max_u32_e32 v29, v21, v25
	v_max_u32_dpp v26, v26, v26 quad_perm:[1,0,3,2] row_mask:0xf bank_mask:0xf
	v_max_u32_dpp v27, v27, v27 quad_perm:[1,0,3,2] row_mask:0xf bank_mask:0xf
	v_max_u32_dpp v28, v28, v28 quad_perm:[1,0,3,2] row_mask:0xf bank_mask:0xf
	v_max_u32_dpp v29, v29, v29 quad_perm:[1,0,3,2] row_mask:0xf bank_mask:0xf
	v_max_u32_dpp v26, v26, v26 quad_perm:[2,3,0,1] row_mask:0xf bank_mask:0xf
	v_max_u32_dpp v27, v27, v27 quad_perm:[2,3,0,1] row_mask:0xf bank_mask:0xf
	v_max_u32_dpp v28, v28, v28 quad_perm:[2,3,0,1] row_mask:0xf bank_mask:0xf
	v_max_u32_dpp v29, v29, v29 quad_perm:[2,3,0,1] row_mask:0xf bank_mask:0xf
	v_max_u32_dpp v26, v26, v26 row_half_mirror row_mask:0xf bank_mask:0xf
	v_max_u32_dpp v27, v27, v27 row_half_mirror row_mask:0xf bank_mask:0xf
	v_max_u32_dpp v28, v28, v28 row_half_mirror row_mask:0xf bank_mask:0xf
	v_max_u32_dpp v29, v29, v29 row_half_mirror row_mask:0xf bank_mask:0xf
	v_max_u32_dpp v26, v26, v26 row_mirror row_mask:0xf bank_mask:0xf
	v_max_u32_dpp v27, v27, v27 row_mirror row_mask:0xf bank_mask:0xf
	v_max_u32_dpp v28, v28, v28 row_mirror row_mask:0xf bank_mask:0xf
	v_max_u32_dpp v29, v29, v29 row_mirror row_mask:0xf bank_mask:0xf
	v_max_u32_dpp v26, v26, v26 row_bcast:15 row_mask:0xa bank_mask:0xf
	v_max_u32_dpp v27, v27, v27 row_bcast:15 row_mask:0xa bank_mask:0xf
; __device__ __forceinline__ void nsa_quad_pre(int bg, int quad, const bf16_t* Q, const bf16_t* KV, const bf16_t* KCMP, const bf16_t* VCMPT, const float* GN, bf16_t* ONSA, ...
;     ...
;             for (int it = 0; it < 13; ++it) {
;                 unsigned m = k0 > k1 ? k0 : k1;
; #pragma unroll
;                 for (int off = 32; off >= 1; off >>= 1) { const unsigned o = (unsigned)__shfl_xor((int)m, off); m = o > m ? o : m; }
;                 if (k0 == m) k0 = 0u; if (k1 == m) k1 = 0u;
;                 if (lane == 0) selq[tt * 16 + it] = 127 - (int)(m & 127u);
	v_max_u32_dpp v28, v28, v28 row_bcast:15 row_mask:0xa bank_mask:0xf
	v_max_u32_dpp v29, v29, v29 row_bcast:15 row_mask:0xa bank_mask:0xf
	v_max_u32_dpp v26, v26, v26 row_bcast:31 row_mask:0xc bank_mask:0xf
	v_max_u32_dpp v27, v27, v27 row_bcast:31 row_mask:0xc bank_mask:0xf
	v_max_u32_dpp v28, v28, v28 row_bcast:31 row_mask:0xc bank_mask:0xf
	v_max_u32_dpp v29, v29, v29 row_bcast:31 row_mask:0xc bank_mask:0xf
	v_readlane_b32 s14, v26, 63
	v_readlane_b32 s15, v27, 63
	v_readlane_b32 s34, v28, 63
	v_readlane_b32 s35, v29, 63
	v_writelane_b32 v82, s14, 2
	v_writelane_b32 v83, s15, 2
	v_writelane_b32 v84, s34, 2
	v_writelane_b32 v85, s35, 2
	v_cmp_ne_u32_e64 s[42:43], s14, v18
	v_cmp_ne_u32_e64 s[66:67], s14, v22
	v_cmp_ne_u32_e64 s[0:1], s15, v19
	v_cmp_ne_u32_e32 vcc, s15, v23
	v_cndmask_b32_e64 v18, 0, v18, s[42:43]
	v_cndmask_b32_e64 v22, 0, v22, s[66:67]
	v_cndmask_b32_e64 v19, 0, v19, s[0:1]
	v_cndmask_b32_e32 v23, 0, v23, vcc
	v_cmp_ne_u32_e64 s[42:43], s34, v20
	v_cmp_ne_u32_e64 s[66:67], s34, v24
	v_cmp_ne_u32_e64 s[0:1], s35, v21
	v_cmp_ne_u32_e32 vcc, s35, v25
	v_cndmask_b32_e64 v20, 0, v20, s[42:43]
	v_cndmask_b32_e64 v24, 0, v24, s[66:67]
	v_cndmask_b32_e64 v21, 0, v21, s[0:1]
	v_cndmask_b32_e32 v25, 0, v25, vcc
	v_max_u32_e32 v26, v18, v22
	v_max_u32_e32 v27, v19, v23
	v_max_u32_e32 v28, v20, v24
	v_max_u32_e32 v29, v21, v25
	v_max_u32_dpp v26, v26, v26 quad_perm:[1,0,3,2] row_mask:0xf bank_mask:0xf
	v_max_u32_dpp v27, v27, v27 quad_perm:[1,0,3,2] row_mask:0xf bank_mask:0xf
	v_max_u32_dpp v28, v28, v28 quad_perm:[1,0,3,2] row_mask:0xf bank_mask:0xf
	v_max_u32_dpp v29, v29, v29 quad_perm:[1,0,3,2] row_mask:0xf bank_mask:0xf
	v_max_u32_dpp v26, v26, v26 quad_perm:[2,3,0,1] row_mask:0xf bank_mask:0xf
	v_max_u32_dpp v27, v27, v27 quad_perm:[2,3,0,1] row_mask:0xf bank_mask:0xf
	v_max_u32_dpp v28, v28, v28 quad_perm:[2,3,0,1] row_mask:0xf bank_mask:0xf
	v_max_u32_dpp v29, v29, v29 quad_perm:[2,3,0,1] row_mask:0xf bank_mask:0xf
	v_max_u32_dpp v26, v26, v26 row_half_mirror row_mask:0xf bank_mask:0xf
	v_max_u32_dpp v27, v27, v27 row_half_mirror row_mask:0xf bank_mask:0xf
	v_max_u32_dpp v28, v28, v28 row_half_mirror row_mask:0xf bank_mask:0xf
	v_max_u32_dpp v29, v29, v29 row_half_mirror row_mask:0xf bank_mask:0xf
	v_max_u32_dpp v26, v26, v26 row_mirror row_mask:0xf bank_mask:0xf
	v_max_u32_dpp v27, v27, v27 row_mirror row_mask:0xf bank_mask:0xf
	v_max_u32_dpp v28, v28, v28 row_mirror row_mask:0xf bank_mask:0xf
	v_max_u32_dpp v29, v29, v29 row_mirror row_mask:0xf bank_mask:0xf
	v_max_u32_dpp v26, v26, v26 row_bcast:15 row_mask:0xa bank_mask:0xf
	v_max_u32_dpp v27, v27, v27 row_bcast:15 row_mask:0xa bank_mask:0xf
	v_max_u32_dpp v28, v28, v28 row_bcast:15 row_mask:0xa bank_mask:0xf
	v_max_u32_dpp v29, v29, v29 row_bcast:15 row_mask:0xa bank_mask:0xf
	v_max_u32_dpp v26, v26, v26 row_bcast:31 row_mask:0xc bank_mask:0xf
	v_max_u32_dpp v27, v27, v27 row_bcast:31 row_mask:0xc bank_mask:0xf
	v_max_u32_dpp v28, v28, v28 row_bcast:31 row_mask:0xc bank_mask:0xf
	v_max_u32_dpp v29, v29, v29 row_bcast:31 row_mask:0xc bank_mask:0xf
	v_readlane_b32 s14, v26, 63
	v_readlane_b32 s15, v27, 63
	v_readlane_b32 s34, v28, 63
	v_readlane_b32 s35, v29, 63
	v_writelane_b32 v82, s14, 3
	v_writelane_b32 v83, s15, 3
	v_writelane_b32 v84, s34, 3
	v_writelane_b32 v85, s35, 3
	v_cmp_ne_u32_e64 s[42:43], s14, v18
	v_cmp_ne_u32_e64 s[66:67], s14, v22
	v_cmp_ne_u32_e64 s[0:1], s15, v19
	v_cmp_ne_u32_e32 vcc, s15, v23
	v_cndmask_b32_e64 v18, 0, v18, s[42:43]
	v_cndmask_b32_e64 v22, 0, v22, s[66:67]
	v_cndmask_b32_e64 v19, 0, v19, s[0:1]
	v_cndmask_b32_e32 v23, 0, v23, vcc
	v_cmp_ne_u32_e64 s[42:43], s34, v20
	v_cmp_ne_u32_e64 s[66:67], s34, v24
	v_cmp_ne_u32_e64 s[0:1], s35, v21
	v_cmp_ne_u32_e32 vcc, s35, v25
	v_cndmask_b32_e64 v20, 0, v20, s[42:43]
	v_cndmask_b32_e64 v24, 0, v24, s[66:67]
	v_cndmask_b32_e64 v21, 0, v21, s[0:1]
	v_cndmask_b32_e32 v25, 0, v25, vcc
	v_max_u32_e32 v26, v18, v22
	v_max_u32_e32 v27, v19, v23
	v_max_u32_e32 v28, v20, v24
	v_max_u32_e32 v29, v21, v25
	v_max_u32_dpp v26, v26, v26 quad_perm:[1,0,3,2] row_mask:0xf bank_mask:0xf
	v_max_u32_dpp v27, v27, v27 quad_perm:[1,0,3,2] row_mask:0xf bank_mask:0xf
	v_max_u32_dpp v28, v28, v28 quad_perm:[1,0,3,2] row_mask:0xf bank_mask:0xf
	v_max_u32_dpp v29, v29, v29 quad_perm:[1,0,3,2] row_mask:0xf bank_mask:0xf
	v_max_u32_dpp v26, v26, v26 quad_perm:[2,3,0,1] row_mask:0xf bank_mask:0xf
	v_max_u32_dpp v27, v27, v27 quad_perm:[2,3,0,1] row_mask:0xf bank_mask:0xf
	v_max_u32_dpp v28, v28, v28 quad_perm:[2,3,0,1] row_mask:0xf bank_mask:0xf
	v_max_u32_dpp v29, v29, v29 quad_perm:[2,3,0,1] row_mask:0xf bank_mask:0xf
	v_max_u32_dpp v26, v26, v26 row_half_mirror row_mask:0xf bank_mask:0xf
	v_max_u32_dpp v27, v27, v27 row_half_mirror row_mask:0xf bank_mask:0xf
	v_max_u32_dpp v28, v28, v28 row_half_mirror row_mask:0xf bank_mask:0xf
	v_max_u32_dpp v29, v29, v29 row_half_mirror row_mask:0xf bank_mask:0xf
	v_max_u32_dpp v26, v26, v26 row_mirror row_mask:0xf bank_mask:0xf
	v_max_u32_dpp v27, v27, v27 row_mirror row_mask:0xf bank_mask:0xf
	v_max_u32_dpp v28, v28, v28 row_mirror row_mask:0xf bank_mask:0xf
	v_max_u32_dpp v29, v29, v29 row_mirror row_mask:0xf bank_mask:0xf
	v_max_u32_dpp v26, v26, v26 row_bcast:15 row_mask:0xa bank_mask:0xf
	v_max_u32_dpp v27, v27, v27 row_bcast:15 row_mask:0xa bank_mask:0xf
	v_max_u32_dpp v28, v28, v28 row_bcast:15 row_mask:0xa bank_mask:0xf
	v_max_u32_dpp v29, v29, v29 row_bcast:15 row_mask:0xa bank_mask:0xf
	v_max_u32_dpp v26, v26, v26 row_bcast:31 row_mask:0xc bank_mask:0xf
	v_max_u32_dpp v27, v27, v27 row_bcast:31 row_mask:0xc bank_mask:0xf
	v_max_u32_dpp v28, v28, v28 row_bcast:31 row_mask:0xc bank_mask:0xf
; __device__ __forceinline__ void nsa_quad_pre(int bg, int quad, const bf16_t* Q, const bf16_t* KV, const bf16_t* KCMP, const bf16_t* VCMPT, const float* GN, bf16_t* ONSA, ...
;     ...
;             for (int it = 0; it < 13; ++it) {
;                 unsigned m = k0 > k1 ? k0 : k1;
; #pragma unroll
;                 for (int off = 32; off >= 1; off >>= 1) { const unsigned o = (unsigned)__shfl_xor((int)m, off); m = o > m ? o : m; }
;                 if (k0 == m) k0 = 0u; if (k1 == m) k1 = 0u;
;                 if (lane == 0) selq[tt * 16 + it] = 127 - (int)(m & 127u);
	v_max_u32_dpp v29, v29, v29 row_bcast:31 row_mask:0xc bank_mask:0xf
	v_readlane_b32 s14, v26, 63
	v_readlane_b32 s15, v27, 63
	v_readlane_b32 s34, v28, 63
	v_readlane_b32 s35, v29, 63
	v_writelane_b32 v82, s14, 4
	v_writelane_b32 v83, s15, 4
	v_writelane_b32 v84, s34, 4
	v_writelane_b32 v85, s35, 4
	v_cmp_ne_u32_e64 s[42:43], s14, v18
	v_cmp_ne_u32_e64 s[66:67], s14, v22
	v_cmp_ne_u32_e64 s[0:1], s15, v19
	v_cmp_ne_u32_e32 vcc, s15, v23
	v_cndmask_b32_e64 v18, 0, v18, s[42:43]
	v_cndmask_b32_e64 v22, 0, v22, s[66:67]
	v_cndmask_b32_e64 v19, 0, v19, s[0:1]
	v_cndmask_b32_e32 v23, 0, v23, vcc
	v_cmp_ne_u32_e64 s[42:43], s34, v20
	v_cmp_ne_u32_e64 s[66:67], s34, v24
	v_cmp_ne_u32_e64 s[0:1], s35, v21
	v_cmp_ne_u32_e32 vcc, s35, v25
	v_cndmask_b32_e64 v20, 0, v20, s[42:43]
	v_cndmask_b32_e64 v24, 0, v24, s[66:67]
	v_cndmask_b32_e64 v21, 0, v21, s[0:1]
	v_cndmask_b32_e32 v25, 0, v25, vcc
	v_max_u32_e32 v26, v18, v22
	v_max_u32_e32 v27, v19, v23
	v_max_u32_e32 v28, v20, v24
	v_max_u32_e32 v29, v21, v25
	v_max_u32_dpp v26, v26, v26 quad_perm:[1,0,3,2] row_mask:0xf bank_mask:0xf
	v_max_u32_dpp v27, v27, v27 quad_perm:[1,0,3,2] row_mask:0xf bank_mask:0xf
	v_max_u32_dpp v28, v28, v28 quad_perm:[1,0,3,2] row_mask:0xf bank_mask:0xf
	v_max_u32_dpp v29, v29, v29 quad_perm:[1,0,3,2] row_mask:0xf bank_mask:0xf
	v_max_u32_dpp v26, v26, v26 quad_perm:[2,3,0,1] row_mask:0xf bank_mask:0xf
	v_max_u32_dpp v27, v27, v27 quad_perm:[2,3,0,1] row_mask:0xf bank_mask:0xf
	v_max_u32_dpp v28, v28, v28 quad_perm:[2,3,0,1] row_mask:0xf bank_mask:0xf
	v_max_u32_dpp v29, v29, v29 quad_perm:[2,3,0,1] row_mask:0xf bank_mask:0xf
	v_max_u32_dpp v26, v26, v26 row_half_mirror row_mask:0xf bank_mask:0xf
	v_max_u32_dpp v27, v27, v27 row_half_mirror row_mask:0xf bank_mask:0xf
	v_max_u32_dpp v28, v28, v28 row_half_mirror row_mask:0xf bank_mask:0xf
	v_max_u32_dpp v29, v29, v29 row_half_mirror row_mask:0xf bank_mask:0xf
	v_max_u32_dpp v26, v26, v26 row_mirror row_mask:0xf bank_mask:0xf
	v_max_u32_dpp v27, v27, v27 row_mirror row_mask:0xf bank_mask:0xf
	v_max_u32_dpp v28, v28, v28 row_mirror row_mask:0xf bank_mask:0xf
	v_max_u32_dpp v29, v29, v29 row_mirror row_mask:0xf bank_mask:0xf
	v_max_u32_dpp v26, v26, v26 row_bcast:15 row_mask:0xa bank_mask:0xf
	v_max_u32_dpp v27, v27, v27 row_bcast:15 row_mask:0xa bank_mask:0xf
	v_max_u32_dpp v28, v28, v28 row_bcast:15 row_mask:0xa bank_mask:0xf
	v_max_u32_dpp v29, v29, v29 row_bcast:15 row_mask:0xa bank_mask:0xf
	v_max_u32_dpp v26, v26, v26 row_bcast:31 row_mask:0xc bank_mask:0xf
	v_max_u32_dpp v27, v27, v27 row_bcast:31 row_mask:0xc bank_mask:0xf
	v_max_u32_dpp v28, v28, v28 row_bcast:31 row_mask:0xc bank_mask:0xf
	v_max_u32_dpp v29, v29, v29 row_bcast:31 row_mask:0xc bank_mask:0xf
	v_readlane_b32 s14, v26, 63
	v_readlane_b32 s15, v27, 63
	v_readlane_b32 s34, v28, 63
	v_readlane_b32 s35, v29, 63
	v_writelane_b32 v82, s14, 5
	v_writelane_b32 v83, s15, 5
	v_writelane_b32 v84, s34, 5
	v_writelane_b32 v85, s35, 5
	v_cmp_ne_u32_e64 s[42:43], s14, v18
	v_cmp_ne_u32_e64 s[66:67], s14, v22
	v_cmp_ne_u32_e64 s[0:1], s15, v19
	v_cmp_ne_u32_e32 vcc, s15, v23
	v_cndmask_b32_e64 v18, 0, v18, s[42:43]
	v_cndmask_b32_e64 v22, 0, v22, s[66:67]
	v_cndmask_b32_e64 v19, 0, v19, s[0:1]
	v_cndmask_b32_e32 v23, 0, v23, vcc
	v_cmp_ne_u32_e64 s[42:43], s34, v20
	v_cmp_ne_u32_e64 s[66:67], s34, v24
	v_cmp_ne_u32_e64 s[0:1], s35, v21
	v_cmp_ne_u32_e32 vcc, s35, v25
	v_cndmask_b32_e64 v20, 0, v20, s[42:43]
	v_cndmask_b32_e64 v24, 0, v24, s[66:67]
	v_cndmask_b32_e64 v21, 0, v21, s[0:1]
	v_cndmask_b32_e32 v25, 0, v25, vcc
	v_max_u32_e32 v26, v18, v22
	v_max_u32_e32 v27, v19, v23
	v_max_u32_e32 v28, v20, v24
	v_max_u32_e32 v29, v21, v25
	v_max_u32_dpp v26, v26, v26 quad_perm:[1,0,3,2] row_mask:0xf bank_mask:0xf
	v_max_u32_dpp v27, v27, v27 quad_perm:[1,0,3,2] row_mask:0xf bank_mask:0xf
	v_max_u32_dpp v28, v28, v28 quad_perm:[1,0,3,2] row_mask:0xf bank_mask:0xf
	v_max_u32_dpp v29, v29, v29 quad_perm:[1,0,3,2] row_mask:0xf bank_mask:0xf
	v_max_u32_dpp v26, v26, v26 quad_perm:[2,3,0,1] row_mask:0xf bank_mask:0xf
	v_max_u32_dpp v27, v27, v27 quad_perm:[2,3,0,1] row_mask:0xf bank_mask:0xf
	v_max_u32_dpp v28, v28, v28 quad_perm:[2,3,0,1] row_mask:0xf bank_mask:0xf
	v_max_u32_dpp v29, v29, v29 quad_perm:[2,3,0,1] row_mask:0xf bank_mask:0xf
	v_max_u32_dpp v26, v26, v26 row_half_mirror row_mask:0xf bank_mask:0xf
	v_max_u32_dpp v27, v27, v27 row_half_mirror row_mask:0xf bank_mask:0xf
	v_max_u32_dpp v28, v28, v28 row_half_mirror row_mask:0xf bank_mask:0xf
	v_max_u32_dpp v29, v29, v29 row_half_mirror row_mask:0xf bank_mask:0xf
	v_max_u32_dpp v26, v26, v26 row_mirror row_mask:0xf bank_mask:0xf
	v_max_u32_dpp v27, v27, v27 row_mirror row_mask:0xf bank_mask:0xf
	v_max_u32_dpp v28, v28, v28 row_mirror row_mask:0xf bank_mask:0xf
	v_max_u32_dpp v29, v29, v29 row_mirror row_mask:0xf bank_mask:0xf
	v_max_u32_dpp v26, v26, v26 row_bcast:15 row_mask:0xa bank_mask:0xf
	v_max_u32_dpp v27, v27, v27 row_bcast:15 row_mask:0xa bank_mask:0xf
	v_max_u32_dpp v28, v28, v28 row_bcast:15 row_mask:0xa bank_mask:0xf
	v_max_u32_dpp v29, v29, v29 row_bcast:15 row_mask:0xa bank_mask:0xf
	v_max_u32_dpp v26, v26, v26 row_bcast:31 row_mask:0xc bank_mask:0xf
	v_max_u32_dpp v27, v27, v27 row_bcast:31 row_mask:0xc bank_mask:0xf
	v_max_u32_dpp v28, v28, v28 row_bcast:31 row_mask:0xc bank_mask:0xf
	v_max_u32_dpp v29, v29, v29 row_bcast:31 row_mask:0xc bank_mask:0xf
	v_readlane_b32 s14, v26, 63
	v_readlane_b32 s15, v27, 63
	v_readlane_b32 s34, v28, 63
	v_readlane_b32 s35, v29, 63
	v_writelane_b32 v82, s14, 6
	v_writelane_b32 v83, s15, 6
	v_writelane_b32 v84, s34, 6
	v_writelane_b32 v85, s35, 6
	v_cmp_ne_u32_e64 s[42:43], s14, v18
; __device__ __forceinline__ void nsa_quad_pre(int bg, int quad, const bf16_t* Q, const bf16_t* KV, const bf16_t* KCMP, const bf16_t* VCMPT, const float* GN, bf16_t* ONSA, ...
;     ...
;             for (int it = 0; it < 13; ++it) {
;                 unsigned m = k0 > k1 ? k0 : k1;
; #pragma unroll
;                 for (int off = 32; off >= 1; off >>= 1) { const unsigned o = (unsigned)__shfl_xor((int)m, off); m = o > m ? o : m; }
;                 if (k0 == m) k0 = 0u; if (k1 == m) k1 = 0u;
;                 if (lane == 0) selq[tt * 16 + it] = 127 - (int)(m & 127u);
	v_cmp_ne_u32_e64 s[66:67], s14, v22
	v_cmp_ne_u32_e64 s[0:1], s15, v19
	v_cmp_ne_u32_e32 vcc, s15, v23
	v_cndmask_b32_e64 v18, 0, v18, s[42:43]
	v_cndmask_b32_e64 v22, 0, v22, s[66:67]
	v_cndmask_b32_e64 v19, 0, v19, s[0:1]
	v_cndmask_b32_e32 v23, 0, v23, vcc
	v_cmp_ne_u32_e64 s[42:43], s34, v20
	v_cmp_ne_u32_e64 s[66:67], s34, v24
	v_cmp_ne_u32_e64 s[0:1], s35, v21
	v_cmp_ne_u32_e32 vcc, s35, v25
	v_cndmask_b32_e64 v20, 0, v20, s[42:43]
	v_cndmask_b32_e64 v24, 0, v24, s[66:67]
	v_cndmask_b32_e64 v21, 0, v21, s[0:1]
	v_cndmask_b32_e32 v25, 0, v25, vcc
	v_max_u32_e32 v26, v18, v22
	v_max_u32_e32 v27, v19, v23
	v_max_u32_e32 v28, v20, v24
	v_max_u32_e32 v29, v21, v25
	v_max_u32_dpp v26, v26, v26 quad_perm:[1,0,3,2] row_mask:0xf bank_mask:0xf
	v_max_u32_dpp v27, v27, v27 quad_perm:[1,0,3,2] row_mask:0xf bank_mask:0xf
	v_max_u32_dpp v28, v28, v28 quad_perm:[1,0,3,2] row_mask:0xf bank_mask:0xf
	v_max_u32_dpp v29, v29, v29 quad_perm:[1,0,3,2] row_mask:0xf bank_mask:0xf
	v_max_u32_dpp v26, v26, v26 quad_perm:[2,3,0,1] row_mask:0xf bank_mask:0xf
	v_max_u32_dpp v27, v27, v27 quad_perm:[2,3,0,1] row_mask:0xf bank_mask:0xf
	v_max_u32_dpp v28, v28, v28 quad_perm:[2,3,0,1] row_mask:0xf bank_mask:0xf
	v_max_u32_dpp v29, v29, v29 quad_perm:[2,3,0,1] row_mask:0xf bank_mask:0xf
	v_max_u32_dpp v26, v26, v26 row_half_mirror row_mask:0xf bank_mask:0xf
	v_max_u32_dpp v27, v27, v27 row_half_mirror row_mask:0xf bank_mask:0xf
	v_max_u32_dpp v28, v28, v28 row_half_mirror row_mask:0xf bank_mask:0xf
	v_max_u32_dpp v29, v29, v29 row_half_mirror row_mask:0xf bank_mask:0xf
	v_max_u32_dpp v26, v26, v26 row_mirror row_mask:0xf bank_mask:0xf
	v_max_u32_dpp v27, v27, v27 row_mirror row_mask:0xf bank_mask:0xf
	v_max_u32_dpp v28, v28, v28 row_mirror row_mask:0xf bank_mask:0xf
	v_max_u32_dpp v29, v29, v29 row_mirror row_mask:0xf bank_mask:0xf
	v_max_u32_dpp v26, v26, v26 row_bcast:15 row_mask:0xa bank_mask:0xf
	v_max_u32_dpp v27, v27, v27 row_bcast:15 row_mask:0xa bank_mask:0xf
	v_max_u32_dpp v28, v28, v28 row_bcast:15 row_mask:0xa bank_mask:0xf
	v_max_u32_dpp v29, v29, v29 row_bcast:15 row_mask:0xa bank_mask:0xf
	v_max_u32_dpp v26, v26, v26 row_bcast:31 row_mask:0xc bank_mask:0xf
	v_max_u32_dpp v27, v27, v27 row_bcast:31 row_mask:0xc bank_mask:0xf
	v_max_u32_dpp v28, v28, v28 row_bcast:31 row_mask:0xc bank_mask:0xf
	v_max_u32_dpp v29, v29, v29 row_bcast:31 row_mask:0xc bank_mask:0xf
	v_readlane_b32 s14, v26, 63
	v_readlane_b32 s15, v27, 63
	v_readlane_b32 s34, v28, 63
	v_readlane_b32 s35, v29, 63
	v_writelane_b32 v82, s14, 7
	v_writelane_b32 v83, s15, 7
	v_writelane_b32 v84, s34, 7
	v_writelane_b32 v85, s35, 7
	v_cmp_ne_u32_e64 s[42:43], s14, v18
	v_cmp_ne_u32_e64 s[66:67], s14, v22
	v_cmp_ne_u32_e64 s[0:1], s15, v19
	v_cmp_ne_u32_e32 vcc, s15, v23
	v_cndmask_b32_e64 v18, 0, v18, s[42:43]
	v_cndmask_b32_e64 v22, 0, v22, s[66:67]
	v_cndmask_b32_e64 v19, 0, v19, s[0:1]
	v_cndmask_b32_e32 v23, 0, v23, vcc
	v_cmp_ne_u32_e64 s[42:43], s34, v20
	v_cmp_ne_u32_e64 s[66:67], s34, v24
	v_cmp_ne_u32_e64 s[0:1], s35, v21
	v_cmp_ne_u32_e32 vcc, s35, v25
	v_cndmask_b32_e64 v20, 0, v20, s[42:43]
	v_cndmask_b32_e64 v24, 0, v24, s[66:67]
	v_cndmask_b32_e64 v21, 0, v21, s[0:1]
	v_cndmask_b32_e32 v25, 0, v25, vcc
	v_max_u32_e32 v26, v18, v22
	v_max_u32_e32 v27, v19, v23
	v_max_u32_e32 v28, v20, v24
	v_max_u32_e32 v29, v21, v25
	v_max_u32_dpp v26, v26, v26 quad_perm:[1,0,3,2] row_mask:0xf bank_mask:0xf
	v_max_u32_dpp v27, v27, v27 quad_perm:[1,0,3,2] row_mask:0xf bank_mask:0xf
	v_max_u32_dpp v28, v28, v28 quad_perm:[1,0,3,2] row_mask:0xf bank_mask:0xf
	v_max_u32_dpp v29, v29, v29 quad_perm:[1,0,3,2] row_mask:0xf bank_mask:0xf
	v_max_u32_dpp v26, v26, v26 quad_perm:[2,3,0,1] row_mask:0xf bank_mask:0xf
	v_max_u32_dpp v27, v27, v27 quad_perm:[2,3,0,1] row_mask:0xf bank_mask:0xf
	v_max_u32_dpp v28, v28, v28 quad_perm:[2,3,0,1] row_mask:0xf bank_mask:0xf
	v_max_u32_dpp v29, v29, v29 quad_perm:[2,3,0,1] row_mask:0xf bank_mask:0xf
	v_max_u32_dpp v26, v26, v26 row_half_mirror row_mask:0xf bank_mask:0xf
	v_max_u32_dpp v27, v27, v27 row_half_mirror row_mask:0xf bank_mask:0xf
	v_max_u32_dpp v28, v28, v28 row_half_mirror row_mask:0xf bank_mask:0xf
	v_max_u32_dpp v29, v29, v29 row_half_mirror row_mask:0xf bank_mask:0xf
	v_max_u32_dpp v26, v26, v26 row_mirror row_mask:0xf bank_mask:0xf
	v_max_u32_dpp v27, v27, v27 row_mirror row_mask:0xf bank_mask:0xf
	v_max_u32_dpp v28, v28, v28 row_mirror row_mask:0xf bank_mask:0xf
	v_max_u32_dpp v29, v29, v29 row_mirror row_mask:0xf bank_mask:0xf
	v_max_u32_dpp v26, v26, v26 row_bcast:15 row_mask:0xa bank_mask:0xf
	v_max_u32_dpp v27, v27, v27 row_bcast:15 row_mask:0xa bank_mask:0xf
	v_max_u32_dpp v28, v28, v28 row_bcast:15 row_mask:0xa bank_mask:0xf
	v_max_u32_dpp v29, v29, v29 row_bcast:15 row_mask:0xa bank_mask:0xf
	v_max_u32_dpp v26, v26, v26 row_bcast:31 row_mask:0xc bank_mask:0xf
	v_max_u32_dpp v27, v27, v27 row_bcast:31 row_mask:0xc bank_mask:0xf
	v_max_u32_dpp v28, v28, v28 row_bcast:31 row_mask:0xc bank_mask:0xf
	v_max_u32_dpp v29, v29, v29 row_bcast:31 row_mask:0xc bank_mask:0xf
	v_readlane_b32 s14, v26, 63
	v_readlane_b32 s15, v27, 63
	v_readlane_b32 s34, v28, 63
	v_readlane_b32 s35, v29, 63
	v_writelane_b32 v82, s14, 8
	v_writelane_b32 v83, s15, 8
	v_writelane_b32 v84, s34, 8
	v_writelane_b32 v85, s35, 8
	v_cmp_ne_u32_e64 s[42:43], s14, v18
	v_cmp_ne_u32_e64 s[66:67], s14, v22
	v_cmp_ne_u32_e64 s[0:1], s15, v19
	v_cmp_ne_u32_e32 vcc, s15, v23
	v_cndmask_b32_e64 v18, 0, v18, s[42:43]
	v_cndmask_b32_e64 v22, 0, v22, s[66:67]
	v_cndmask_b32_e64 v19, 0, v19, s[0:1]
	v_cndmask_b32_e32 v23, 0, v23, vcc
	v_cmp_ne_u32_e64 s[42:43], s34, v20
	v_cmp_ne_u32_e64 s[66:67], s34, v24
; __device__ __forceinline__ void nsa_quad_pre(int bg, int quad, const bf16_t* Q, const bf16_t* KV, const bf16_t* KCMP, const bf16_t* VCMPT, const float* GN, bf16_t* ONSA, ...
;     ...
;             for (int it = 0; it < 13; ++it) {
;                 unsigned m = k0 > k1 ? k0 : k1;
; #pragma unroll
;                 for (int off = 32; off >= 1; off >>= 1) { const unsigned o = (unsigned)__shfl_xor((int)m, off); m = o > m ? o : m; }
;                 if (k0 == m) k0 = 0u; if (k1 == m) k1 = 0u;
;                 if (lane == 0) selq[tt * 16 + it] = 127 - (int)(m & 127u);
	v_cmp_ne_u32_e64 s[0:1], s35, v21
	v_cmp_ne_u32_e32 vcc, s35, v25
	v_cndmask_b32_e64 v20, 0, v20, s[42:43]
	v_cndmask_b32_e64 v24, 0, v24, s[66:67]
	v_cndmask_b32_e64 v21, 0, v21, s[0:1]
	v_cndmask_b32_e32 v25, 0, v25, vcc
	v_max_u32_e32 v26, v18, v22
	v_max_u32_e32 v27, v19, v23
	v_max_u32_e32 v28, v20, v24
	v_max_u32_e32 v29, v21, v25
	v_max_u32_dpp v26, v26, v26 quad_perm:[1,0,3,2] row_mask:0xf bank_mask:0xf
	v_max_u32_dpp v27, v27, v27 quad_perm:[1,0,3,2] row_mask:0xf bank_mask:0xf
	v_max_u32_dpp v28, v28, v28 quad_perm:[1,0,3,2] row_mask:0xf bank_mask:0xf
	v_max_u32_dpp v29, v29, v29 quad_perm:[1,0,3,2] row_mask:0xf bank_mask:0xf
	v_max_u32_dpp v26, v26, v26 quad_perm:[2,3,0,1] row_mask:0xf bank_mask:0xf
	v_max_u32_dpp v27, v27, v27 quad_perm:[2,3,0,1] row_mask:0xf bank_mask:0xf
	v_max_u32_dpp v28, v28, v28 quad_perm:[2,3,0,1] row_mask:0xf bank_mask:0xf
	v_max_u32_dpp v29, v29, v29 quad_perm:[2,3,0,1] row_mask:0xf bank_mask:0xf
	v_max_u32_dpp v26, v26, v26 row_half_mirror row_mask:0xf bank_mask:0xf
	v_max_u32_dpp v27, v27, v27 row_half_mirror row_mask:0xf bank_mask:0xf
	v_max_u32_dpp v28, v28, v28 row_half_mirror row_mask:0xf bank_mask:0xf
	v_max_u32_dpp v29, v29, v29 row_half_mirror row_mask:0xf bank_mask:0xf
	v_max_u32_dpp v26, v26, v26 row_mirror row_mask:0xf bank_mask:0xf
	v_max_u32_dpp v27, v27, v27 row_mirror row_mask:0xf bank_mask:0xf
	v_max_u32_dpp v28, v28, v28 row_mirror row_mask:0xf bank_mask:0xf
	v_max_u32_dpp v29, v29, v29 row_mirror row_mask:0xf bank_mask:0xf
	v_max_u32_dpp v26, v26, v26 row_bcast:15 row_mask:0xa bank_mask:0xf
	v_max_u32_dpp v27, v27, v27 row_bcast:15 row_mask:0xa bank_mask:0xf
	v_max_u32_dpp v28, v28, v28 row_bcast:15 row_mask:0xa bank_mask:0xf
	v_max_u32_dpp v29, v29, v29 row_bcast:15 row_mask:0xa bank_mask:0xf
	v_max_u32_dpp v26, v26, v26 row_bcast:31 row_mask:0xc bank_mask:0xf
	v_max_u32_dpp v27, v27, v27 row_bcast:31 row_mask:0xc bank_mask:0xf
	v_max_u32_dpp v28, v28, v28 row_bcast:31 row_mask:0xc bank_mask:0xf
	v_max_u32_dpp v29, v29, v29 row_bcast:31 row_mask:0xc bank_mask:0xf
	v_readlane_b32 s14, v26, 63
	v_readlane_b32 s15, v27, 63
	v_readlane_b32 s34, v28, 63
	v_readlane_b32 s35, v29, 63
	v_writelane_b32 v82, s14, 9
	v_writelane_b32 v83, s15, 9
	v_writelane_b32 v84, s34, 9
	v_writelane_b32 v85, s35, 9
	v_cmp_ne_u32_e64 s[42:43], s14, v18
	v_cmp_ne_u32_e64 s[66:67], s14, v22
	v_cmp_ne_u32_e64 s[0:1], s15, v19
	v_cmp_ne_u32_e32 vcc, s15, v23
	v_cndmask_b32_e64 v18, 0, v18, s[42:43]
	v_cndmask_b32_e64 v22, 0, v22, s[66:67]
	v_cndmask_b32_e64 v19, 0, v19, s[0:1]
	v_cndmask_b32_e32 v23, 0, v23, vcc
	v_cmp_ne_u32_e64 s[42:43], s34, v20
	v_cmp_ne_u32_e64 s[66:67], s34, v24
	v_cmp_ne_u32_e64 s[0:1], s35, v21
	v_cmp_ne_u32_e32 vcc, s35, v25
	v_cndmask_b32_e64 v20, 0, v20, s[42:43]
	v_cndmask_b32_e64 v24, 0, v24, s[66:67]
	v_cndmask_b32_e64 v21, 0, v21, s[0:1]
	v_cndmask_b32_e32 v25, 0, v25, vcc
	v_max_u32_e32 v26, v18, v22
	v_max_u32_e32 v27, v19, v23
	v_max_u32_e32 v28, v20, v24
	v_max_u32_e32 v29, v21, v25
	v_max_u32_dpp v26, v26, v26 quad_perm:[1,0,3,2] row_mask:0xf bank_mask:0xf
	v_max_u32_dpp v27, v27, v27 quad_perm:[1,0,3,2] row_mask:0xf bank_mask:0xf
	v_max_u32_dpp v28, v28, v28 quad_perm:[1,0,3,2] row_mask:0xf bank_mask:0xf
	v_max_u32_dpp v29, v29, v29 quad_perm:[1,0,3,2] row_mask:0xf bank_mask:0xf
	v_max_u32_dpp v26, v26, v26 quad_perm:[2,3,0,1] row_mask:0xf bank_mask:0xf
	v_max_u32_dpp v27, v27, v27 quad_perm:[2,3,0,1] row_mask:0xf bank_mask:0xf
	v_max_u32_dpp v28, v28, v28 quad_perm:[2,3,0,1] row_mask:0xf bank_mask:0xf
	v_max_u32_dpp v29, v29, v29 quad_perm:[2,3,0,1] row_mask:0xf bank_mask:0xf
	v_max_u32_dpp v26, v26, v26 row_half_mirror row_mask:0xf bank_mask:0xf
	v_max_u32_dpp v27, v27, v27 row_half_mirror row_mask:0xf bank_mask:0xf
	v_max_u32_dpp v28, v28, v28 row_half_mirror row_mask:0xf bank_mask:0xf
	v_max_u32_dpp v29, v29, v29 row_half_mirror row_mask:0xf bank_mask:0xf
	v_max_u32_dpp v26, v26, v26 row_mirror row_mask:0xf bank_mask:0xf
	v_max_u32_dpp v27, v27, v27 row_mirror row_mask:0xf bank_mask:0xf
	v_max_u32_dpp v28, v28, v28 row_mirror row_mask:0xf bank_mask:0xf
	v_max_u32_dpp v29, v29, v29 row_mirror row_mask:0xf bank_mask:0xf
	v_max_u32_dpp v26, v26, v26 row_bcast:15 row_mask:0xa bank_mask:0xf
	v_max_u32_dpp v27, v27, v27 row_bcast:15 row_mask:0xa bank_mask:0xf
	v_max_u32_dpp v28, v28, v28 row_bcast:15 row_mask:0xa bank_mask:0xf
	v_max_u32_dpp v29, v29, v29 row_bcast:15 row_mask:0xa bank_mask:0xf
	v_max_u32_dpp v26, v26, v26 row_bcast:31 row_mask:0xc bank_mask:0xf
	v_max_u32_dpp v27, v27, v27 row_bcast:31 row_mask:0xc bank_mask:0xf
	v_max_u32_dpp v28, v28, v28 row_bcast:31 row_mask:0xc bank_mask:0xf
	v_max_u32_dpp v29, v29, v29 row_bcast:31 row_mask:0xc bank_mask:0xf
	v_readlane_b32 s14, v26, 63
	v_readlane_b32 s15, v27, 63
	v_readlane_b32 s34, v28, 63
	v_readlane_b32 s35, v29, 63
	v_writelane_b32 v82, s14, 10
	v_writelane_b32 v83, s15, 10
	v_writelane_b32 v84, s34, 10
	v_writelane_b32 v85, s35, 10
	v_cmp_ne_u32_e64 s[42:43], s14, v18
	v_cmp_ne_u32_e64 s[66:67], s14, v22
	v_cmp_ne_u32_e64 s[0:1], s15, v19
	v_cmp_ne_u32_e32 vcc, s15, v23
	v_cndmask_b32_e64 v18, 0, v18, s[42:43]
	v_cndmask_b32_e64 v22, 0, v22, s[66:67]
	v_cndmask_b32_e64 v19, 0, v19, s[0:1]
	v_cndmask_b32_e32 v23, 0, v23, vcc
	v_cmp_ne_u32_e64 s[42:43], s34, v20
	v_cmp_ne_u32_e64 s[66:67], s34, v24
	v_cmp_ne_u32_e64 s[0:1], s35, v21
	v_cmp_ne_u32_e32 vcc, s35, v25
	v_cndmask_b32_e64 v20, 0, v20, s[42:43]
	v_cndmask_b32_e64 v24, 0, v24, s[66:67]
	v_cndmask_b32_e64 v21, 0, v21, s[0:1]
	v_cndmask_b32_e32 v25, 0, v25, vcc
	v_max_u32_e32 v26, v18, v22
	v_max_u32_e32 v27, v19, v23
	v_max_u32_e32 v28, v20, v24
; __device__ __forceinline__ void nsa_quad_pre(int bg, int quad, const bf16_t* Q, const bf16_t* KV, const bf16_t* KCMP, const bf16_t* VCMPT, const float* GN, bf16_t* ONSA, ...
;     ...
;             for (int it = 0; it < 13; ++it) {
;                 unsigned m = k0 > k1 ? k0 : k1;
; #pragma unroll
;                 for (int off = 32; off >= 1; off >>= 1) { const unsigned o = (unsigned)__shfl_xor((int)m, off); m = o > m ? o : m; }
;                 if (k0 == m) k0 = 0u; if (k1 == m) k1 = 0u;
;                 if (lane == 0) selq[tt * 16 + it] = 127 - (int)(m & 127u);
;             }
;             if (lane == 0) { selq[tt * 16 + 13] = 0; selq[tt * 16 + 14] = cur - 1; selq[tt * 16 + 15] = cur; }
	v_max_u32_e32 v29, v21, v25
	v_max_u32_dpp v26, v26, v26 quad_perm:[1,0,3,2] row_mask:0xf bank_mask:0xf
	v_max_u32_dpp v27, v27, v27 quad_perm:[1,0,3,2] row_mask:0xf bank_mask:0xf
	v_max_u32_dpp v28, v28, v28 quad_perm:[1,0,3,2] row_mask:0xf bank_mask:0xf
	v_max_u32_dpp v29, v29, v29 quad_perm:[1,0,3,2] row_mask:0xf bank_mask:0xf
	v_max_u32_dpp v26, v26, v26 quad_perm:[2,3,0,1] row_mask:0xf bank_mask:0xf
	v_max_u32_dpp v27, v27, v27 quad_perm:[2,3,0,1] row_mask:0xf bank_mask:0xf
	v_max_u32_dpp v28, v28, v28 quad_perm:[2,3,0,1] row_mask:0xf bank_mask:0xf
	v_max_u32_dpp v29, v29, v29 quad_perm:[2,3,0,1] row_mask:0xf bank_mask:0xf
	v_max_u32_dpp v26, v26, v26 row_half_mirror row_mask:0xf bank_mask:0xf
	v_max_u32_dpp v27, v27, v27 row_half_mirror row_mask:0xf bank_mask:0xf
	v_max_u32_dpp v28, v28, v28 row_half_mirror row_mask:0xf bank_mask:0xf
	v_max_u32_dpp v29, v29, v29 row_half_mirror row_mask:0xf bank_mask:0xf
	v_max_u32_dpp v26, v26, v26 row_mirror row_mask:0xf bank_mask:0xf
	v_max_u32_dpp v27, v27, v27 row_mirror row_mask:0xf bank_mask:0xf
	v_max_u32_dpp v28, v28, v28 row_mirror row_mask:0xf bank_mask:0xf
	v_max_u32_dpp v29, v29, v29 row_mirror row_mask:0xf bank_mask:0xf
	v_max_u32_dpp v26, v26, v26 row_bcast:15 row_mask:0xa bank_mask:0xf
	v_max_u32_dpp v27, v27, v27 row_bcast:15 row_mask:0xa bank_mask:0xf
	v_max_u32_dpp v28, v28, v28 row_bcast:15 row_mask:0xa bank_mask:0xf
	v_max_u32_dpp v29, v29, v29 row_bcast:15 row_mask:0xa bank_mask:0xf
	v_max_u32_dpp v26, v26, v26 row_bcast:31 row_mask:0xc bank_mask:0xf
	v_max_u32_dpp v27, v27, v27 row_bcast:31 row_mask:0xc bank_mask:0xf
	v_max_u32_dpp v28, v28, v28 row_bcast:31 row_mask:0xc bank_mask:0xf
	v_max_u32_dpp v29, v29, v29 row_bcast:31 row_mask:0xc bank_mask:0xf
	v_readlane_b32 s14, v26, 63
	v_readlane_b32 s15, v27, 63
	v_readlane_b32 s34, v28, 63
	v_readlane_b32 s35, v29, 63
	v_writelane_b32 v82, s14, 11
	v_writelane_b32 v83, s15, 11
	v_writelane_b32 v84, s34, 11
	v_writelane_b32 v85, s35, 11
	v_cmp_ne_u32_e64 s[42:43], s14, v18
	v_cmp_ne_u32_e64 s[66:67], s14, v22
	v_cmp_ne_u32_e64 s[0:1], s15, v19
	v_cmp_ne_u32_e32 vcc, s15, v23
	v_cndmask_b32_e64 v18, 0, v18, s[42:43]
	v_cndmask_b32_e64 v22, 0, v22, s[66:67]
	v_cndmask_b32_e64 v19, 0, v19, s[0:1]
	v_cndmask_b32_e32 v23, 0, v23, vcc
	v_cmp_ne_u32_e64 s[42:43], s34, v20
	v_cmp_ne_u32_e64 s[66:67], s34, v24
	v_cmp_ne_u32_e64 s[0:1], s35, v21
	v_cmp_ne_u32_e32 vcc, s35, v25
	v_cndmask_b32_e64 v20, 0, v20, s[42:43]
	v_cndmask_b32_e64 v24, 0, v24, s[66:67]
	v_cndmask_b32_e64 v21, 0, v21, s[0:1]
	v_cndmask_b32_e32 v25, 0, v25, vcc
	v_max_u32_e32 v26, v18, v22
	v_max_u32_e32 v27, v19, v23
	v_max_u32_e32 v28, v20, v24
	v_max_u32_e32 v29, v21, v25
	v_max_u32_dpp v26, v26, v26 quad_perm:[1,0,3,2] row_mask:0xf bank_mask:0xf
	v_max_u32_dpp v27, v27, v27 quad_perm:[1,0,3,2] row_mask:0xf bank_mask:0xf
	v_max_u32_dpp v28, v28, v28 quad_perm:[1,0,3,2] row_mask:0xf bank_mask:0xf
	v_max_u32_dpp v29, v29, v29 quad_perm:[1,0,3,2] row_mask:0xf bank_mask:0xf
	v_max_u32_dpp v26, v26, v26 quad_perm:[2,3,0,1] row_mask:0xf bank_mask:0xf
	v_max_u32_dpp v27, v27, v27 quad_perm:[2,3,0,1] row_mask:0xf bank_mask:0xf
	v_max_u32_dpp v28, v28, v28 quad_perm:[2,3,0,1] row_mask:0xf bank_mask:0xf
	v_max_u32_dpp v29, v29, v29 quad_perm:[2,3,0,1] row_mask:0xf bank_mask:0xf
	v_max_u32_dpp v26, v26, v26 row_half_mirror row_mask:0xf bank_mask:0xf
	v_max_u32_dpp v27, v27, v27 row_half_mirror row_mask:0xf bank_mask:0xf
	v_max_u32_dpp v28, v28, v28 row_half_mirror row_mask:0xf bank_mask:0xf
	v_max_u32_dpp v29, v29, v29 row_half_mirror row_mask:0xf bank_mask:0xf
	v_max_u32_dpp v26, v26, v26 row_mirror row_mask:0xf bank_mask:0xf
	v_max_u32_dpp v27, v27, v27 row_mirror row_mask:0xf bank_mask:0xf
	v_max_u32_dpp v28, v28, v28 row_mirror row_mask:0xf bank_mask:0xf
	v_max_u32_dpp v29, v29, v29 row_mirror row_mask:0xf bank_mask:0xf
	v_max_u32_dpp v26, v26, v26 row_bcast:15 row_mask:0xa bank_mask:0xf
	v_max_u32_dpp v27, v27, v27 row_bcast:15 row_mask:0xa bank_mask:0xf
	v_max_u32_dpp v28, v28, v28 row_bcast:15 row_mask:0xa bank_mask:0xf
	v_max_u32_dpp v29, v29, v29 row_bcast:15 row_mask:0xa bank_mask:0xf
	v_max_u32_dpp v26, v26, v26 row_bcast:31 row_mask:0xc bank_mask:0xf
	v_max_u32_dpp v27, v27, v27 row_bcast:31 row_mask:0xc bank_mask:0xf
	v_max_u32_dpp v28, v28, v28 row_bcast:31 row_mask:0xc bank_mask:0xf
	v_max_u32_dpp v29, v29, v29 row_bcast:31 row_mask:0xc bank_mask:0xf
	v_readlane_b32 s14, v26, 63
	v_readlane_b32 s15, v27, 63
	v_readlane_b32 s34, v28, 63
	v_readlane_b32 s35, v29, 63
	v_writelane_b32 v82, s14, 12
	v_writelane_b32 v83, s15, 12
	v_writelane_b32 v84, s34, 12
	v_writelane_b32 v85, s35, 12
	v_and_b32_e32 v82, 127, v82
	v_sub_u32_e32 v82, 127, v82
	v_and_b32_e32 v83, 127, v83
	v_sub_u32_e32 v83, 127, v83
	v_and_b32_e32 v84, 127, v84
	v_sub_u32_e32 v84, 127, v84
	v_and_b32_e32 v85, 127, v85
	v_sub_u32_e32 v85, 127, v85
	s_add_i32 s19, s18, -1
	v_mov_b32_e32 v236, s19
	v_mov_b32_e32 v237, s18
	v_cmp_eq_u32_e64 s[14:15], 14, v184
	v_cmp_eq_u32_e64 s[34:35], 15, v184
	s_nop 0
	v_cndmask_b32_e64 v82, v82, v236, s[14:15]
	v_cndmask_b32_e64 v82, v82, v237, s[34:35]
	v_cndmask_b32_e64 v83, v83, v236, s[14:15]
	v_cndmask_b32_e64 v83, v83, v237, s[34:35]
	v_cndmask_b32_e64 v84, v84, v236, s[14:15]
	v_cndmask_b32_e64 v84, v84, v237, s[34:35]
	v_cndmask_b32_e64 v85, v85, v236, s[14:15]
	v_cndmask_b32_e64 v85, v85, v237, s[34:35]
	s_and_saveexec_b64 s[42:43], s[6:7]
	ds_write_b32 v196, v82 offset:51520
	ds_write_b32 v196, v83 offset:51584
	ds_write_b32 v196, v84 offset:51648
	ds_write_b32 v196, v85 offset:51712
	s_or_b64 exec, exec, s[42:43]
	s_branch .Ltopk_done_q1

; template <int MODE> ...
;     ...
;     for (int jA = j0, pp = 0; jA <= qb; jA += 2, pp ^= 1) {
;       for (int sub = 0; sub < 2; ++sub) {
;         const int j = jA + sub; if (j > qb) break;
;         const bool pre = j + 2 <= qb;
;         if (pre) NSA_LD1(j + 2);
;         const LAS bf16_t* Ks = stage + pp * 18432 + sub * 9216; const LAS bf16_t* Vs = Ks + 4608;
;         const bool far = MODE == 0 && (qb - j >= 17);
; #pragma unroll
;         for (int tile = 0; tile < 2; ++tile) {
;             const int tl0 = wave * 8 + tile * 4, t0 = qb * 64 + tl0;
;             unsigned mb[4] = {1u, 1u, 1u, 1u};
;             if (MODE == 0) {
; #pragma unroll
;                 for (int i = 0; i < 4; ++i) mb[i] = (masks[(tl0 + i) * 4 + (j >> 5)] >> (j & 31)) & 1u; }
;             if (MODE == 1 || __builtin_amdgcn_readfirstlane((int)(mb[0] | mb[1] | mb[2] | mb[3]))) {
;                 f32x4 sc[4];
; #pragma unroll
;                 for (int cc = 0; cc < 4; ++cc) { const LAS bf16_t* kp = Ks + (cc * 16 + r16) * 72 + q4 * 8;
;                     sc[cc] = MFMA16(aq[tile][0], *(const LAS bf16x8*)kp, z4); sc[cc] = MFMA16(aq[tile][1], *(const LAS bf16x8*)(kp + 32), sc[cc]); }
;                 if (far) {
; #pragma unroll
;                     for (int cc = 0; cc < 4; ++cc)
; #pragma unroll
;                         for (int i = 0; i < 4; ++i) { const float p = mb[i] ? ex2(sc[cc][i] + bfar) : 0.f; ls[tile][i] += p; Pb[(4 * q4 + i) * 72 + cc * 16 + r16] = tobf(p); }
;                 } else {
; #pragma unroll
;                     for (int cc = 0; cc < 4; ++cc) { const int pos = j * 64 + cc * 16 + r16;
; #pragma unroll
;                         for (int i = 0; i < 4; ++i) { const int dist = t0 + i - pos; const bool ok = MODE ? ((unsigned)dist < 512u) : (dist >= 0 && mb[i]);
;                             const float p = ok ? ex2(sc[cc][i] + bt[clampd(dist)]) : 0.f; ls[tile][i] += p; Pb[(4 * q4 + i) * 72 + cc * 16 + r16] = tobf(p); } }
;                 }
;                 CBAR();
; #pragma unroll
;                 for (int ks = 0; ks < 2; ++ks) { const bf16x8 aP = *(const LAS bf16x8*)(Pb + r16 * 72 + ks * 32 + q4 * 8);
; #pragma unroll
;                     for (int nt = 0; nt < 4; ++nt) os[tile][nt] = MFMA16(aP, *(const LAS bf16x8*)(Vs + (nt * 16 + r16) * 72 + ks * 32 + q4 * 8), os[tile][nt]); }
;                 CBAR();
;             }
;         }
.Lnsa_blkend_16:
	s_mov_b32 s93, s94
	s_mov_b32 s94, s95
	s_add_i32 s57, s57, 1
	s_cmp_lt_u32 s57, s92
	s_waitcnt vmcnt(2) lgkmcnt(0)
	s_barrier
	s_cbranch_scc1 .Lnsa_blk_loop
	s_cmp_eq_u32 s43, 0
	s_cbranch_scc1 .Lnsa_pvnone_25
	ds_read_b128 v[50:53], v172 offset:0
	ds_read_b128 v[54:57], v173 offset:0
	ds_read_b128 v[58:61], v172 offset:2048
	ds_read_b128 v[62:65], v173 offset:2048
	s_cmp_eq_u32 s43, 3
	s_cbranch_scc0 .Lnsa_pvone_26
	s_waitcnt lgkmcnt(2)
	v_mfma_f32_16x16x32_bf16 v[2:5], v[50:53], v[82:85], v[2:5]
	v_mfma_f32_16x16x32_bf16 v[2:5], v[54:57], v[86:89], v[2:5]
	v_mfma_f32_16x16x32_bf16 v[18:21], v[50:53], v[90:93], v[18:21]
	v_mfma_f32_16x16x32_bf16 v[18:21], v[54:57], v[94:97], v[18:21]
	ds_read_b128 v[50:53], v172 offset:4096
	ds_read_b128 v[54:57], v173 offset:4096
	s_waitcnt lgkmcnt(2)
	v_mfma_f32_16x16x32_bf16 v[6:9], v[58:61], v[82:85], v[6:9]
	v_mfma_f32_16x16x32_bf16 v[6:9], v[62:65], v[86:89], v[6:9]
	v_mfma_f32_16x16x32_bf16 v[22:25], v[58:61], v[90:93], v[22:25]
	v_mfma_f32_16x16x32_bf16 v[22:25], v[62:65], v[94:97], v[22:25]
	ds_read_b128 v[58:61], v172 offset:6144
	ds_read_b128 v[62:65], v173 offset:6144
	s_waitcnt lgkmcnt(2)
	v_mfma_f32_16x16x32_bf16 v[10:13], v[50:53], v[82:85], v[10:13]
	v_mfma_f32_16x16x32_bf16 v[10:13], v[54:57], v[86:89], v[10:13]
	v_mfma_f32_16x16x32_bf16 v[26:29], v[50:53], v[90:93], v[26:29]
	v_mfma_f32_16x16x32_bf16 v[26:29], v[54:57], v[94:97], v[26:29]
	s_waitcnt lgkmcnt(0)
	v_mfma_f32_16x16x32_bf16 v[14:17], v[58:61], v[82:85], v[14:17]
	v_mfma_f32_16x16x32_bf16 v[14:17], v[62:65], v[86:89], v[14:17]
	v_mfma_f32_16x16x32_bf16 v[30:33], v[58:61], v[90:93], v[30:33]
	v_mfma_f32_16x16x32_bf16 v[30:33], v[62:65], v[94:97], v[30:33]
	s_branch .Lnsa_pvend_28
